# rotation extended: K-loop body scalar head also before the loop-back barrier; phase-2 address VALU moved before its barrier
# speedup vs baseline: 1.0139x; 1.0017x over previous
; #define PG8_STAGE(bufoff, gbase, v0, v1) do { \
;         __builtin_amdgcn_global_load_lds((const unsigned*)((const char*)(gbase) + (v0)), (LAS unsigned*)(lds + (bufoff) + ldsw), 16, 0, 0); \
;         __builtin_amdgcn_global_load_lds((const unsigned*)((const char*)(gbase) + (v1)), (LAS unsigned*)(lds + (bufoff) + ldsw + 8192), 16, 0, 0); } while (0)
; #define PG8_LDA(dst, b, h) do { _Pragma("unroll") for (int m = 0; m < 4; ++m) _Pragma("unroll") for (int k = 0; k < 2; ++k) dst[m][k] = *(const LAS bf16x8*)(lds + PG8_SA(b, h) + aoff + m * 2048 + k * 1024); } while (0)
; #define PG8_LDB(dst, b, h) do { _Pragma("unroll") for (int n = 0; n < 2; ++n) _Pragma("unroll") for (int k = 0; k < 2; ++k) dst[n][k] = *(const LAS bf16x8*)(lds + PG8_SB(b, h) + boff + n * 2048 + k * 1024); } while (0)
; #define PG8_MMA(ai, bj, At, Bt) do { __builtin_amdgcn_s_setprio(1); _Pragma("unroll") for (int m = 0; m < 4; ++m) _Pragma("unroll") for (int n = 0; n < 2; ++n) _Pragma("unroll") for (int k = 0; k < 2; ++k) \
;         acc[ai][bj][m][n] = __builtin_amdgcn_mfma_f32_16x16x32_bf16(Bt[n][k], At[m][k], acc[ai][bj][m][n], 0, 0, 0); __builtin_amdgcn_s_setprio(0); } while (0)
; #define PG8_WAIT_V(n) asm volatile("s_waitcnt vmcnt(" #n ")" ::: "memory")
; #define PG8_WAIT_L(n) asm volatile("s_waitcnt lgkmcnt(" #n ")" ::: "memory")
; #define PG8_BAR __builtin_amdgcn_s_barrier()
; #define PG8_SCHED __builtin_amdgcn_sched_barrier(0)
; template <class Epi, class Sched>
; __device__ __forceinline__ void gemm_phase(LAS unsigned char* lds, const Sched& S, const Epi& E) {
;     ...
;             PG8_LDB(B0, 0, 0); PG8_SCHED; PG8_LDA(At, 0, 0); PG8_STAGE(PG8_SA(1, 1), a1 + hA, vA0, vA1);
;             PG8_WAIT_L(8); PG8_BAR; PG8_WAIT_L(0); PG8_MMA(0, 0, At, B0); PG8_BAR; PG8_SCHED;
;             PG8_LDB(B1, 0, 1); PG8_STAGE(PG8_SB(0, 0), b2, xB0, xB1);
;             PG8_BAR; PG8_WAIT_L(0); PG8_MMA(0, 1, At, B1); PG8_BAR;
;             PG8_LDA(At, 0, 1); PG8_STAGE(PG8_SA(0, 0), a2, xA0, xA1);
;             PG8_BAR; PG8_WAIT_L(0); PG8_MMA(1, 0, At, B0); PG8_BAR; PG8_SCHED;
;             PG8_STAGE(PG8_SB(0, 1), b2 + xhB, xB0, xB1);
;             PG8_WAIT_V(6); PG8_BAR; PG8_MMA(1, 1, At, B1); PG8_BAR;
.Lrot_body_0:
	ds_read_b128 v[158:161], v138
	ds_read_b128 v[182:185], v138 offset:1024
	ds_read_b128 v[186:189], v138 offset:2048
	ds_read_b128 v[190:193], v138 offset:3072
	v_lshl_add_u64 v[226:227], s[26:27], 0, v[132:133]
	s_add_i32 m0, s48, 0xc000
	ds_read_b128 v[194:197], v154
	ds_read_b128 v[198:201], v154 offset:1024
	ds_read_b128 v[202:205], v154 offset:2048
	ds_read_b128 v[206:209], v154 offset:3072
	ds_read_b128 v[210:213], v154 offset:4096
	ds_read_b128 v[214:217], v154 offset:5120
	ds_read_b128 v[218:221], v154 offset:6144
	ds_read_b128 v[222:225], v154 offset:7168
	global_load_lds_dwordx4 v[226:227], off
	v_lshl_add_u64 v[226:227], s[26:27], 0, v[134:135]
	s_add_i32 m0, s48, 0xe000
	s_nop 0
	global_load_lds_dwordx4 v[226:227], off
	s_waitcnt lgkmcnt(8)
	s_barrier
	s_waitcnt lgkmcnt(0)
	v_mfma_f32_16x16x32_bf16 v[124:127], v[158:161], v[194:197], v[124:127]
	v_mfma_f32_16x16x32_bf16 v[120:123], v[186:189], v[194:197], v[120:123]
	v_mfma_f32_16x16x32_bf16 v[116:119], v[158:161], v[202:205], v[116:119]
	v_mfma_f32_16x16x32_bf16 v[112:115], v[186:189], v[202:205], v[112:115]
	v_mfma_f32_16x16x32_bf16 v[100:103], v[158:161], v[210:213], v[100:103]
	v_mfma_f32_16x16x32_bf16 v[96:99], v[186:189], v[210:213], v[96:99]
	v_mfma_f32_16x16x32_bf16 v[84:87], v[158:161], v[218:221], v[84:87]
	v_mfma_f32_16x16x32_bf16 v[80:83], v[186:189], v[218:221], v[80:83]
	v_mfma_f32_16x16x32_bf16 v[124:127], v[182:185], v[198:201], v[124:127]
	v_mfma_f32_16x16x32_bf16 v[120:123], v[190:193], v[198:201], v[120:123]
	v_mfma_f32_16x16x32_bf16 v[116:119], v[182:185], v[206:209], v[116:119]
	v_mfma_f32_16x16x32_bf16 v[112:115], v[190:193], v[206:209], v[112:115]
	v_mfma_f32_16x16x32_bf16 v[100:103], v[182:185], v[214:217], v[100:103]
	v_mfma_f32_16x16x32_bf16 v[96:99], v[190:193], v[214:217], v[96:99]
	v_mfma_f32_16x16x32_bf16 v[84:87], v[182:185], v[222:225], v[84:87]
	v_mfma_f32_16x16x32_bf16 v[80:83], v[190:193], v[222:225], v[80:83]
	s_barrier
	s_add_i32 s69, 0, 0x14000
	s_add_i32 s21, s21, s43
	v_add_u32_e32 v138, s69, v153
	s_mov_b32 m0, s21
	ds_read_b128 v[226:229], v138
	ds_read_b128 v[230:233], v138 offset:1024
	ds_read_b128 v[234:237], v138 offset:2048
	ds_read_b128 v[238:241], v138 offset:3072
	global_load_lds_dwordx4 v136, s[38:39]
	s_add_i32 m0, s21, 0x2000
	v_mov_b32_e32 v147, v137
	global_load_lds_dwordx4 v146, s[38:39]
	v_lshl_add_u64 v[242:243], s[38:39], 0, v[136:137]
	v_lshl_add_u64 v[244:245], s[38:39], 0, v[146:147]
	s_barrier
	s_waitcnt lgkmcnt(0)
	v_mfma_f32_16x16x32_bf16 v[108:111], v[226:229], v[194:197], v[108:111]
	v_mfma_f32_16x16x32_bf16 v[104:107], v[234:237], v[194:197], v[104:107]
	v_mfma_f32_16x16x32_bf16 v[92:95], v[226:229], v[202:205], v[92:95]
	v_mfma_f32_16x16x32_bf16 v[88:91], v[234:237], v[202:205], v[88:91]
	v_mfma_f32_16x16x32_bf16 v[76:79], v[226:229], v[210:213], v[76:79]
	v_mfma_f32_16x16x32_bf16 v[72:75], v[234:237], v[210:213], v[72:75]
	v_mfma_f32_16x16x32_bf16 v[68:71], v[226:229], v[218:221], v[68:71]
	v_mfma_f32_16x16x32_bf16 v[64:67], v[234:237], v[218:221], v[64:67]
	v_mfma_f32_16x16x32_bf16 v[108:111], v[230:233], v[198:201], v[108:111]
	v_mfma_f32_16x16x32_bf16 v[104:107], v[238:241], v[198:201], v[104:107]
	v_mfma_f32_16x16x32_bf16 v[92:95], v[230:233], v[206:209], v[92:95]
	v_mfma_f32_16x16x32_bf16 v[88:91], v[238:241], v[206:209], v[88:91]
	v_mfma_f32_16x16x32_bf16 v[76:79], v[230:233], v[214:217], v[76:79]
	v_mfma_f32_16x16x32_bf16 v[72:75], v[238:241], v[214:217], v[72:75]
	v_mfma_f32_16x16x32_bf16 v[68:71], v[230:233], v[222:225], v[68:71]
	v_mfma_f32_16x16x32_bf16 v[64:67], v[238:241], v[222:225], v[64:67]
	s_mov_b32 m0, s48
	v_lshl_add_u64 v[246:247], s[40:41], 0, v[150:151]
	s_barrier
	ds_read_b128 v[194:197], v154 offset:16384
	ds_read_b128 v[198:201], v154 offset:17408
	ds_read_b128 v[202:205], v154 offset:18432
	ds_read_b128 v[206:209], v154 offset:19456
	ds_read_b128 v[210:213], v154 offset:20480
	ds_read_b128 v[214:217], v154 offset:21504
	ds_read_b128 v[218:221], v154 offset:22528
	ds_read_b128 v[222:225], v154 offset:23552
	global_load_lds_dwordx4 v[246:247], off
	v_lshl_add_u64 v[248:249], s[40:41], 0, v[148:149]
	s_mov_b32 m0, s49
	s_nop 0
	global_load_lds_dwordx4 v[248:249], off
	s_barrier
	s_waitcnt lgkmcnt(0)
	v_mfma_f32_16x16x32_bf16 v[60:63], v[158:161], v[194:197], v[60:63]
	v_mfma_f32_16x16x32_bf16 v[56:59], v[186:189], v[194:197], v[56:59]
	v_mfma_f32_16x16x32_bf16 v[52:55], v[158:161], v[202:205], v[52:55]
	v_mfma_f32_16x16x32_bf16 v[44:47], v[186:189], v[202:205], v[44:47]
	v_mfma_f32_16x16x32_bf16 v[36:39], v[158:161], v[210:213], v[36:39]
	v_mfma_f32_16x16x32_bf16 v[28:31], v[186:189], v[210:213], v[28:31]
	v_mfma_f32_16x16x32_bf16 v[20:23], v[158:161], v[218:221], v[20:23]
	v_mfma_f32_16x16x32_bf16 v[12:15], v[186:189], v[218:221], v[12:15]
	v_mfma_f32_16x16x32_bf16 v[60:63], v[182:185], v[198:201], v[60:63]
	v_mfma_f32_16x16x32_bf16 v[56:59], v[190:193], v[198:201], v[56:59]
	v_mfma_f32_16x16x32_bf16 v[52:55], v[182:185], v[206:209], v[52:55]
	v_mfma_f32_16x16x32_bf16 v[44:47], v[190:193], v[206:209], v[44:47]
	v_mfma_f32_16x16x32_bf16 v[36:39], v[182:185], v[214:217], v[36:39]
	v_mfma_f32_16x16x32_bf16 v[28:31], v[190:193], v[214:217], v[28:31]
	v_mfma_f32_16x16x32_bf16 v[20:23], v[182:185], v[222:225], v[20:23]
	v_mfma_f32_16x16x32_bf16 v[12:15], v[190:193], v[222:225], v[12:15]
	s_barrier
	s_add_u32 s70, s38, 0x80000
	s_addc_u32 s71, s39, 0
	s_add_i32 s21, s69, s43
	s_mov_b32 m0, s21
	s_nop 0
	global_load_lds_dwordx4 v136, s[70:71]
	s_add_i32 m0, s21, 0x2000
	s_nop 0
	global_load_lds_dwordx4 v146, s[70:71]
	s_waitcnt vmcnt(6)
	s_barrier
; #define PG8_STAGE(bufoff, gbase, v0, v1) do { \
;         __builtin_amdgcn_global_load_lds((const unsigned*)((const char*)(gbase) + (v0)), (LAS unsigned*)(lds + (bufoff) + ldsw), 16, 0, 0); \
;         __builtin_amdgcn_global_load_lds((const unsigned*)((const char*)(gbase) + (v1)), (LAS unsigned*)(lds + (bufoff) + ldsw + 8192), 16, 0, 0); } while (0)
; #define PG8_LDA(dst, b, h) do { _Pragma("unroll") for (int m = 0; m < 4; ++m) _Pragma("unroll") for (int k = 0; k < 2; ++k) dst[m][k] = *(const LAS bf16x8*)(lds + PG8_SA(b, h) + aoff + m * 2048 + k * 1024); } while (0)
; #define PG8_LDB(dst, b, h) do { _Pragma("unroll") for (int n = 0; n < 2; ++n) _Pragma("unroll") for (int k = 0; k < 2; ++k) dst[n][k] = *(const LAS bf16x8*)(lds + PG8_SB(b, h) + boff + n * 2048 + k * 1024); } while (0)
; #define PG8_MMA(ai, bj, At, Bt) do { __builtin_amdgcn_s_setprio(1); _Pragma("unroll") for (int m = 0; m < 4; ++m) _Pragma("unroll") for (int n = 0; n < 2; ++n) _Pragma("unroll") for (int k = 0; k < 2; ++k) \
;         acc[ai][bj][m][n] = __builtin_amdgcn_mfma_f32_16x16x32_bf16(Bt[n][k], At[m][k], acc[ai][bj][m][n], 0, 0, 0); __builtin_amdgcn_s_setprio(0); } while (0)
; #define PG8_WAIT_V(n) asm volatile("s_waitcnt vmcnt(" #n ")" ::: "memory")
; #define PG8_WAIT_L(n) asm volatile("s_waitcnt lgkmcnt(" #n ")" ::: "memory")
; #define PG8_BAR __builtin_amdgcn_s_barrier()
; #define PG8_SCHED __builtin_amdgcn_sched_barrier(0)
; template <class Epi, class Sched>
; __device__ __forceinline__ void gemm_phase(LAS unsigned char* lds, const Sched& S, const Epi& E) {
;     ...
;             PG8_WAIT_V(6); PG8_BAR; PG8_MMA(1, 1, At, B1); PG8_BAR;
;             PG8_LDB(B0, 1, 0); PG8_SCHED; PG8_LDA(At, 1, 0); PG8_STAGE(PG8_SA(0, 1), a2 + xhA, xA0, xA1);
;             PG8_WAIT_L(8); PG8_BAR; PG8_WAIT_L(0); PG8_MMA(0, 0, At, B0); PG8_BAR; PG8_SCHED;
;             PG8_LDB(B1, 1, 1); PG8_STAGE(PG8_SB(1, 0), b3, xB0, xB1);
;             PG8_BAR; PG8_WAIT_L(0); PG8_MMA(0, 1, At, B1); PG8_BAR;
;             PG8_LDA(At, 1, 1); PG8_STAGE(PG8_SA(1, 0), a3, xA0, xA1);
;             PG8_BAR; PG8_WAIT_L(0); PG8_MMA(1, 0, At, B0); PG8_BAR; PG8_SCHED;
	v_mfma_f32_16x16x32_bf16 v[48:51], v[226:229], v[194:197], v[48:51]
	v_mfma_f32_16x16x32_bf16 v[40:43], v[234:237], v[194:197], v[40:43]
	v_mfma_f32_16x16x32_bf16 v[32:35], v[226:229], v[202:205], v[32:35]
	v_mfma_f32_16x16x32_bf16 v[24:27], v[234:237], v[202:205], v[24:27]
	v_mfma_f32_16x16x32_bf16 v[16:19], v[226:229], v[210:213], v[16:19]
	v_mfma_f32_16x16x32_bf16 v[8:11], v[234:237], v[210:213], v[8:11]
	v_mfma_f32_16x16x32_bf16 v[4:7], v[226:229], v[218:221], v[4:7]
	v_mfma_f32_16x16x32_bf16 v[0:3], v[234:237], v[218:221], v[0:3]
	v_mfma_f32_16x16x32_bf16 v[48:51], v[230:233], v[198:201], v[48:51]
	v_mfma_f32_16x16x32_bf16 v[40:43], v[238:241], v[198:201], v[40:43]
	v_mfma_f32_16x16x32_bf16 v[32:35], v[230:233], v[206:209], v[32:35]
	v_mfma_f32_16x16x32_bf16 v[24:27], v[238:241], v[206:209], v[24:27]
	v_mfma_f32_16x16x32_bf16 v[16:19], v[230:233], v[214:217], v[16:19]
	v_mfma_f32_16x16x32_bf16 v[8:11], v[238:241], v[214:217], v[8:11]
	v_mfma_f32_16x16x32_bf16 v[4:7], v[230:233], v[222:225], v[4:7]
	v_mfma_f32_16x16x32_bf16 v[0:3], v[238:241], v[222:225], v[0:3]
	s_add_i32 s21, 0, 0x18000
	v_add_u32_e32 v138, s21, v153
	s_barrier
	ds_read_b128 v[158:161], v138
	ds_read_b128 v[182:185], v138 offset:1024
	ds_read_b128 v[186:189], v138 offset:2048
	ds_read_b128 v[190:193], v138 offset:3072
	s_add_u32 s40, s40, 0x80000
	s_addc_u32 s41, s41, 0
	s_mov_b32 m0, s50
	v_lshl_add_u64 v[150:151], s[40:41], 0, v[150:151]
	ds_read_b128 v[194:197], v154 offset:32768
	ds_read_b128 v[198:201], v154 offset:33792
	ds_read_b128 v[202:205], v154 offset:34816
	ds_read_b128 v[206:209], v154 offset:35840
	ds_read_b128 v[210:213], v154 offset:36864
	ds_read_b128 v[214:217], v154 offset:37888
	ds_read_b128 v[218:221], v154 offset:38912
	ds_read_b128 v[222:225], v154 offset:39936
	global_load_lds_dwordx4 v[150:151], off
	v_lshl_add_u64 v[148:149], s[40:41], 0, v[148:149]
	s_mov_b32 m0, s51
	s_nop 0
	global_load_lds_dwordx4 v[148:149], off
	s_waitcnt lgkmcnt(8)
	s_barrier
	s_waitcnt lgkmcnt(0)
	v_mfma_f32_16x16x32_bf16 v[124:127], v[158:161], v[194:197], v[124:127]
	v_mfma_f32_16x16x32_bf16 v[120:123], v[186:189], v[194:197], v[120:123]
	v_mfma_f32_16x16x32_bf16 v[116:119], v[158:161], v[202:205], v[116:119]
	v_mfma_f32_16x16x32_bf16 v[112:115], v[186:189], v[202:205], v[112:115]
	v_mfma_f32_16x16x32_bf16 v[100:103], v[158:161], v[210:213], v[100:103]
	v_mfma_f32_16x16x32_bf16 v[96:99], v[186:189], v[210:213], v[96:99]
	v_mfma_f32_16x16x32_bf16 v[84:87], v[158:161], v[218:221], v[84:87]
	v_mfma_f32_16x16x32_bf16 v[80:83], v[186:189], v[218:221], v[80:83]
	v_mfma_f32_16x16x32_bf16 v[124:127], v[182:185], v[198:201], v[124:127]
	v_mfma_f32_16x16x32_bf16 v[120:123], v[190:193], v[198:201], v[120:123]
	v_mfma_f32_16x16x32_bf16 v[116:119], v[182:185], v[206:209], v[116:119]
	v_mfma_f32_16x16x32_bf16 v[112:115], v[190:193], v[206:209], v[112:115]
	v_mfma_f32_16x16x32_bf16 v[100:103], v[182:185], v[214:217], v[100:103]
	v_mfma_f32_16x16x32_bf16 v[96:99], v[190:193], v[214:217], v[96:99]
	v_mfma_f32_16x16x32_bf16 v[84:87], v[182:185], v[222:225], v[84:87]
	v_mfma_f32_16x16x32_bf16 v[80:83], v[190:193], v[222:225], v[80:83]
	s_barrier
	s_add_i32 s40, 0, 0x1c000
	s_add_i32 s21, s21, s43
	v_add_u32_e32 v138, s40, v153
	v_lshl_add_u64 v[238:239], v[242:243], 0, s[44:45]
	s_mov_b32 m0, s21
	ds_read_b128 v[148:151], v138
	ds_read_b128 v[226:229], v138 offset:1024
	ds_read_b128 v[230:233], v138 offset:2048
	ds_read_b128 v[234:237], v138 offset:3072
	global_load_lds_dwordx4 v[238:239], off
	v_lshl_add_u64 v[238:239], v[244:245], 0, s[44:45]
	s_add_i32 m0, s21, 0x2000
	s_nop 0
	global_load_lds_dwordx4 v[238:239], off
	s_barrier
	s_waitcnt lgkmcnt(0)
	v_mfma_f32_16x16x32_bf16 v[108:111], v[148:151], v[194:197], v[108:111]
	v_mfma_f32_16x16x32_bf16 v[104:107], v[230:233], v[194:197], v[104:107]
	v_mfma_f32_16x16x32_bf16 v[92:95], v[148:151], v[202:205], v[92:95]
	v_mfma_f32_16x16x32_bf16 v[88:91], v[230:233], v[202:205], v[88:91]
	v_mfma_f32_16x16x32_bf16 v[76:79], v[148:151], v[210:213], v[76:79]
	v_mfma_f32_16x16x32_bf16 v[72:75], v[230:233], v[210:213], v[72:75]
	v_mfma_f32_16x16x32_bf16 v[68:71], v[148:151], v[218:221], v[68:71]
	v_mfma_f32_16x16x32_bf16 v[64:67], v[230:233], v[218:221], v[64:67]
	v_mfma_f32_16x16x32_bf16 v[108:111], v[226:229], v[198:201], v[108:111]
	v_mfma_f32_16x16x32_bf16 v[104:107], v[234:237], v[198:201], v[104:107]
	v_mfma_f32_16x16x32_bf16 v[92:95], v[226:229], v[206:209], v[92:95]
	v_mfma_f32_16x16x32_bf16 v[88:91], v[234:237], v[206:209], v[88:91]
	v_mfma_f32_16x16x32_bf16 v[76:79], v[226:229], v[214:217], v[76:79]
	v_mfma_f32_16x16x32_bf16 v[72:75], v[234:237], v[214:217], v[72:75]
	v_mfma_f32_16x16x32_bf16 v[68:71], v[226:229], v[222:225], v[68:71]
	v_mfma_f32_16x16x32_bf16 v[64:67], v[234:237], v[222:225], v[64:67]
	s_mov_b32 m0, s64
	v_lshl_add_u64 v[238:239], v[246:247], 0, s[44:45]
	s_barrier
; #define PG8_STAGE(bufoff, gbase, v0, v1) do { \
;         __builtin_amdgcn_global_load_lds((const unsigned*)((const char*)(gbase) + (v0)), (LAS unsigned*)(lds + (bufoff) + ldsw), 16, 0, 0); \
;         __builtin_amdgcn_global_load_lds((const unsigned*)((const char*)(gbase) + (v1)), (LAS unsigned*)(lds + (bufoff) + ldsw + 8192), 16, 0, 0); } while (0)
; #define PG8_LDA(dst, b, h) do { _Pragma("unroll") for (int m = 0; m < 4; ++m) _Pragma("unroll") for (int k = 0; k < 2; ++k) dst[m][k] = *(const LAS bf16x8*)(lds + PG8_SA(b, h) + aoff + m * 2048 + k * 1024); } while (0)
; #define PG8_MMA(ai, bj, At, Bt) do { __builtin_amdgcn_s_setprio(1); _Pragma("unroll") for (int m = 0; m < 4; ++m) _Pragma("unroll") for (int n = 0; n < 2; ++n) _Pragma("unroll") for (int k = 0; k < 2; ++k) \
;         acc[ai][bj][m][n] = __builtin_amdgcn_mfma_f32_16x16x32_bf16(Bt[n][k], At[m][k], acc[ai][bj][m][n], 0, 0, 0); __builtin_amdgcn_s_setprio(0); } while (0)
; #define PG8_WAIT_V(n) asm volatile("s_waitcnt vmcnt(" #n ")" ::: "memory")
; #define PG8_WAIT_L(n) asm volatile("s_waitcnt lgkmcnt(" #n ")" ::: "memory")
; #define PG8_BAR __builtin_amdgcn_s_barrier()
; #define PG8_SCHED __builtin_amdgcn_sched_barrier(0)
; template <class Epi, class Sched>
; __device__ __forceinline__ void gemm_phase(LAS unsigned char* lds, const Sched& S, const Epi& E) {
;     ...
;         for (int t = 0; t < nt; t += 2) {
;             const bool last = (t == nt - 2);
;             const char* a1 = cA + (size_t)(t + 1) * kstep;
;             const char* a2 = last ? nA : cA + (size_t)(t + 2) * kstep; const char* b2 = last ? nB : cB + (size_t)(t + 2) * kstep;
;             const char* a3 = a2 + kstep; const char* b3 = b2 + kstep;
;             const unsigned xA0 = last ? nvA0 : vA0, xA1 = last ? nvA1 : vA1, xB0 = last ? nvB0 : vB0, xB1 = last ? nvB1 : vB1;
;             const size_t xhA = last ? nhA : hA, xhB = last ? nhB : hB;
;     ...
;             PG8_LDA(At, 1, 1); PG8_STAGE(PG8_SA(1, 0), a3, xA0, xA1);
;             PG8_BAR; PG8_WAIT_L(0); PG8_MMA(1, 0, At, B0); PG8_BAR; PG8_SCHED;
;             PG8_STAGE(PG8_SB(1, 1), b3 + xhB, xB0, xB1);
;             PG8_WAIT_V(6); PG8_BAR; PG8_MMA(1, 1, At, B1); PG8_BAR;
;         }
	ds_read_b128 v[194:197], v154 offset:49152
	ds_read_b128 v[198:201], v154 offset:50176
	ds_read_b128 v[202:205], v154 offset:51200
	ds_read_b128 v[206:209], v154 offset:52224
	ds_read_b128 v[210:213], v154 offset:53248
	ds_read_b128 v[214:217], v154 offset:54272
	ds_read_b128 v[218:221], v154 offset:55296
	ds_read_b128 v[222:225], v154 offset:56320
	global_load_lds_dwordx4 v[238:239], off
	v_lshl_add_u64 v[238:239], v[248:249], 0, s[44:45]
	s_mov_b32 m0, s65
	s_nop 0
	global_load_lds_dwordx4 v[238:239], off
	s_barrier
	s_waitcnt lgkmcnt(0)
	v_mfma_f32_16x16x32_bf16 v[60:63], v[158:161], v[194:197], v[60:63]
	v_mfma_f32_16x16x32_bf16 v[56:59], v[186:189], v[194:197], v[56:59]
	v_mfma_f32_16x16x32_bf16 v[52:55], v[158:161], v[202:205], v[52:55]
	v_mfma_f32_16x16x32_bf16 v[44:47], v[186:189], v[202:205], v[44:47]
	v_mfma_f32_16x16x32_bf16 v[36:39], v[158:161], v[210:213], v[36:39]
	v_mfma_f32_16x16x32_bf16 v[28:31], v[186:189], v[210:213], v[28:31]
	v_mfma_f32_16x16x32_bf16 v[20:23], v[158:161], v[218:221], v[20:23]
	v_mfma_f32_16x16x32_bf16 v[12:15], v[186:189], v[218:221], v[12:15]
	v_mfma_f32_16x16x32_bf16 v[60:63], v[182:185], v[198:201], v[60:63]
	v_mfma_f32_16x16x32_bf16 v[56:59], v[190:193], v[198:201], v[56:59]
	v_mfma_f32_16x16x32_bf16 v[52:55], v[182:185], v[206:209], v[52:55]
	v_mfma_f32_16x16x32_bf16 v[44:47], v[190:193], v[206:209], v[44:47]
	v_mfma_f32_16x16x32_bf16 v[36:39], v[182:185], v[214:217], v[36:39]
	v_mfma_f32_16x16x32_bf16 v[28:31], v[190:193], v[214:217], v[28:31]
	v_mfma_f32_16x16x32_bf16 v[20:23], v[182:185], v[222:225], v[20:23]
	v_mfma_f32_16x16x32_bf16 v[12:15], v[190:193], v[222:225], v[12:15]
	s_barrier
	s_add_u32 s38, s38, 0x80080
	s_addc_u32 s39, s39, 0
	s_add_i32 s21, s40, s43
	s_mov_b32 m0, s21
	s_nop 0
	global_load_lds_dwordx4 v136, s[38:39]
	s_add_i32 m0, s21, 0x2000
	s_nop 0
	global_load_lds_dwordx4 v146, s[38:39]
	s_waitcnt vmcnt(6)
	s_barrier
	v_mfma_f32_16x16x32_bf16 v[48:51], v[148:151], v[194:197], v[48:51]
	v_mfma_f32_16x16x32_bf16 v[40:43], v[230:233], v[194:197], v[40:43]
	v_mfma_f32_16x16x32_bf16 v[32:35], v[148:151], v[202:205], v[32:35]
	v_mfma_f32_16x16x32_bf16 v[24:27], v[230:233], v[202:205], v[24:27]
	v_mfma_f32_16x16x32_bf16 v[16:19], v[148:151], v[210:213], v[16:19]
	v_mfma_f32_16x16x32_bf16 v[8:11], v[230:233], v[210:213], v[8:11]
	v_mfma_f32_16x16x32_bf16 v[4:7], v[148:151], v[218:221], v[4:7]
	v_mfma_f32_16x16x32_bf16 v[0:3], v[230:233], v[218:221], v[0:3]
	v_mfma_f32_16x16x32_bf16 v[48:51], v[226:229], v[198:201], v[48:51]
	v_mfma_f32_16x16x32_bf16 v[40:43], v[234:237], v[198:201], v[40:43]
	v_mfma_f32_16x16x32_bf16 v[32:35], v[226:229], v[206:209], v[32:35]
	v_mfma_f32_16x16x32_bf16 v[24:27], v[234:237], v[206:209], v[24:27]
	v_mfma_f32_16x16x32_bf16 v[16:19], v[226:229], v[214:217], v[16:19]
	v_mfma_f32_16x16x32_bf16 v[8:11], v[234:237], v[214:217], v[8:11]
	v_mfma_f32_16x16x32_bf16 v[4:7], v[226:229], v[222:225], v[4:7]
	v_mfma_f32_16x16x32_bf16 v[0:3], v[234:237], v[222:225], v[0:3]
	s_add_i32 s15, s15, 2
	s_add_u32 s26, s26, 0x100
	s_addc_u32 s27, s27, 0
	s_add_u32 s34, s34, 0x100
	s_addc_u32 s35, s35, 0
	s_cmp_gt_u32 s15, 29
	s_cbranch_scc1 .Lrot_exit_0
	s_cmp_eq_u32 s15, 28
	s_cselect_b64 s[40:41], -1, 0
	s_and_b64 vcc, exec, s[40:41]
	v_mov_b64_e32 v[148:149], v[130:131]
	v_mov_b64_e32 v[150:151], v[128:129]
	v_mov_b32_e32 v146, v156
	v_mov_b32_e32 v136, v155
	s_mov_b64 s[38:39], s[24:25]
	s_cbranch_vccnz .Lrot_join_0
	v_mov_b64_e32 v[148:149], v[134:135]
	v_mov_b64_e32 v[150:151], v[132:133]
	v_mov_b32_e32 v146, v142
	v_mov_b32_e32 v136, v144
	s_mov_b64 s[38:39], s[34:35]
.Lrot_join_0:
	s_add_u32 s21, s26, 0xfff80080
	s_addc_u32 s69, s27, -1
	s_and_b64 s[40:41], exec, s[40:41]
	s_cselect_b32 s41, s23, s69
	s_cselect_b32 s40, s22, s21
	s_add_i32 s21, 0, 0x10000
	v_add_u32_e32 v138, s21, v153
	s_barrier
	s_branch .Lrot_body_0

; #define PG8_STAGE(bufoff, gbase, v0, v1) do { \
;         __builtin_amdgcn_global_load_lds((const unsigned*)((const char*)(gbase) + (v0)), (LAS unsigned*)(lds + (bufoff) + ldsw), 16, 0, 0); \
;         __builtin_amdgcn_global_load_lds((const unsigned*)((const char*)(gbase) + (v1)), (LAS unsigned*)(lds + (bufoff) + ldsw + 8192), 16, 0, 0); } while (0)
; #define PG8_LDA(dst, b, h) do { _Pragma("unroll") for (int m = 0; m < 4; ++m) _Pragma("unroll") for (int k = 0; k < 2; ++k) dst[m][k] = *(const LAS bf16x8*)(lds + PG8_SA(b, h) + aoff + m * 2048 + k * 1024); } while (0)
; #define PG8_LDB(dst, b, h) do { _Pragma("unroll") for (int n = 0; n < 2; ++n) _Pragma("unroll") for (int k = 0; k < 2; ++k) dst[n][k] = *(const LAS bf16x8*)(lds + PG8_SB(b, h) + boff + n * 2048 + k * 1024); } while (0)
; #define PG8_MMA(ai, bj, At, Bt) do { __builtin_amdgcn_s_setprio(1); _Pragma("unroll") for (int m = 0; m < 4; ++m) _Pragma("unroll") for (int n = 0; n < 2; ++n) _Pragma("unroll") for (int k = 0; k < 2; ++k) \
;         acc[ai][bj][m][n] = __builtin_amdgcn_mfma_f32_16x16x32_bf16(Bt[n][k], At[m][k], acc[ai][bj][m][n], 0, 0, 0); __builtin_amdgcn_s_setprio(0); } while (0)
; #define PG8_WAIT_V(n) asm volatile("s_waitcnt vmcnt(" #n ")" ::: "memory")
; #define PG8_WAIT_L(n) asm volatile("s_waitcnt lgkmcnt(" #n ")" ::: "memory")
; #define PG8_BAR __builtin_amdgcn_s_barrier()
; #define PG8_SCHED __builtin_amdgcn_sched_barrier(0)
; template <class Epi, class Sched>
; __device__ __forceinline__ void gemm_phase(LAS unsigned char* lds, const Sched& S, const Epi& E) {
;     ...
;             PG8_LDB(B0, 0, 0); PG8_SCHED; PG8_LDA(At, 0, 0); PG8_STAGE(PG8_SA(1, 1), a1 + hA, vA0, vA1);
;             PG8_WAIT_L(8); PG8_BAR; PG8_WAIT_L(0); PG8_MMA(0, 0, At, B0); PG8_BAR; PG8_SCHED;
;             PG8_LDB(B1, 0, 1); PG8_STAGE(PG8_SB(0, 0), b2, xB0, xB1);
;             PG8_BAR; PG8_WAIT_L(0); PG8_MMA(0, 1, At, B1); PG8_BAR;
;             PG8_LDA(At, 0, 1); PG8_STAGE(PG8_SA(0, 0), a2, xA0, xA1);
;             PG8_BAR; PG8_WAIT_L(0); PG8_MMA(1, 0, At, B0); PG8_BAR; PG8_SCHED;
;             PG8_STAGE(PG8_SB(0, 1), b2 + xhB, xB0, xB1);
;             PG8_WAIT_V(6); PG8_BAR; PG8_MMA(1, 1, At, B1); PG8_BAR;
.Lrot_body_1:
	ds_read_b128 v[158:161], v138
	ds_read_b128 v[186:189], v138 offset:1024
	ds_read_b128 v[190:193], v138 offset:2048
	ds_read_b128 v[194:197], v138 offset:3072
	v_lshl_add_u64 v[230:231], s[34:35], 0, v[134:135]
	s_add_i32 m0, s91, 0xc000
	ds_read_b128 v[198:201], v185
	ds_read_b128 v[202:205], v185 offset:1024
	ds_read_b128 v[206:209], v185 offset:2048
	ds_read_b128 v[210:213], v185 offset:3072
	ds_read_b128 v[214:217], v185 offset:4096
	ds_read_b128 v[218:221], v185 offset:5120
	ds_read_b128 v[222:225], v185 offset:6144
	ds_read_b128 v[226:229], v185 offset:7168
	global_load_lds_dwordx4 v[230:231], off
	v_lshl_add_u64 v[230:231], s[34:35], 0, v[150:151]
	s_add_i32 m0, s91, 0xe000
	s_nop 0
	global_load_lds_dwordx4 v[230:231], off
	s_waitcnt lgkmcnt(8)
	s_barrier
	s_waitcnt lgkmcnt(0)
	v_mfma_f32_16x16x32_bf16 v[124:127], v[158:161], v[198:201], v[124:127]
	v_mfma_f32_16x16x32_bf16 v[120:123], v[190:193], v[198:201], v[120:123]
	v_mfma_f32_16x16x32_bf16 v[116:119], v[158:161], v[206:209], v[116:119]
	v_mfma_f32_16x16x32_bf16 v[112:115], v[190:193], v[206:209], v[112:115]
	v_mfma_f32_16x16x32_bf16 v[108:111], v[158:161], v[214:217], v[108:111]
	v_mfma_f32_16x16x32_bf16 v[104:107], v[190:193], v[214:217], v[104:107]
	v_mfma_f32_16x16x32_bf16 v[100:103], v[158:161], v[222:225], v[100:103]
	v_mfma_f32_16x16x32_bf16 v[96:99], v[190:193], v[222:225], v[96:99]
	v_mfma_f32_16x16x32_bf16 v[124:127], v[186:189], v[202:205], v[124:127]
	v_mfma_f32_16x16x32_bf16 v[120:123], v[194:197], v[202:205], v[120:123]
	v_mfma_f32_16x16x32_bf16 v[116:119], v[186:189], v[210:213], v[116:119]
	v_mfma_f32_16x16x32_bf16 v[112:115], v[194:197], v[210:213], v[112:115]
	v_mfma_f32_16x16x32_bf16 v[108:111], v[186:189], v[218:221], v[108:111]
	v_mfma_f32_16x16x32_bf16 v[104:107], v[194:197], v[218:221], v[104:107]
	v_mfma_f32_16x16x32_bf16 v[100:103], v[186:189], v[226:229], v[100:103]
	v_mfma_f32_16x16x32_bf16 v[96:99], v[194:197], v[226:229], v[96:99]
	s_barrier
	s_add_i32 vcc_lo, 0, 0x14000
	s_add_i32 s65, s65, s9
	v_add_u32_e32 v138, vcc_lo, v184
	s_mov_b32 m0, s65
	ds_read_b128 v[230:233], v138
	ds_read_b128 v[234:237], v138 offset:1024
	ds_read_b128 v[238:241], v138 offset:2048
	ds_read_b128 v[242:245], v138 offset:3072
	global_load_lds_dwordx4 v136, s[92:93]
	s_add_i32 m0, s65, 0x2000
	v_mov_b32_e32 v157, v137
	global_load_lds_dwordx4 v156, s[92:93]
	v_lshl_add_u64 v[246:247], s[92:93], 0, v[136:137]
	v_lshl_add_u64 v[248:249], s[92:93], 0, v[156:157]
	s_barrier
	s_waitcnt lgkmcnt(0)
	v_mfma_f32_16x16x32_bf16 v[92:95], v[230:233], v[198:201], v[92:95]
	v_mfma_f32_16x16x32_bf16 v[88:91], v[238:241], v[198:201], v[88:91]
	v_mfma_f32_16x16x32_bf16 v[84:87], v[230:233], v[206:209], v[84:87]
	v_mfma_f32_16x16x32_bf16 v[80:83], v[238:241], v[206:209], v[80:83]
	v_mfma_f32_16x16x32_bf16 v[76:79], v[230:233], v[214:217], v[76:79]
	v_mfma_f32_16x16x32_bf16 v[72:75], v[238:241], v[214:217], v[72:75]
	v_mfma_f32_16x16x32_bf16 v[68:71], v[230:233], v[222:225], v[68:71]
	v_mfma_f32_16x16x32_bf16 v[64:67], v[238:241], v[222:225], v[64:67]
	v_mfma_f32_16x16x32_bf16 v[92:95], v[234:237], v[202:205], v[92:95]
	v_mfma_f32_16x16x32_bf16 v[88:91], v[242:245], v[202:205], v[88:91]
	v_mfma_f32_16x16x32_bf16 v[84:87], v[234:237], v[210:213], v[84:87]
	v_mfma_f32_16x16x32_bf16 v[80:83], v[242:245], v[210:213], v[80:83]
	v_mfma_f32_16x16x32_bf16 v[76:79], v[234:237], v[218:221], v[76:79]
	v_mfma_f32_16x16x32_bf16 v[72:75], v[242:245], v[218:221], v[72:75]
	v_mfma_f32_16x16x32_bf16 v[68:71], v[234:237], v[226:229], v[68:71]
	v_mfma_f32_16x16x32_bf16 v[64:67], v[242:245], v[226:229], v[64:67]
	s_mov_b32 m0, s91
	v_lshl_add_u64 v[250:251], s[54:55], 0, v[154:155]
	s_barrier
	ds_read_b128 v[198:201], v185 offset:16384
	ds_read_b128 v[202:205], v185 offset:17408
	ds_read_b128 v[206:209], v185 offset:18432
	ds_read_b128 v[210:213], v185 offset:19456
	ds_read_b128 v[214:217], v185 offset:20480
	ds_read_b128 v[218:221], v185 offset:21504
	ds_read_b128 v[222:225], v185 offset:22528
	ds_read_b128 v[226:229], v185 offset:23552
	global_load_lds_dwordx4 v[250:251], off
	v_lshl_add_u64 v[140:141], s[54:55], 0, v[152:153]
	s_mov_b32 m0, s50
	s_nop 0
	global_load_lds_dwordx4 v[140:141], off
	s_barrier
	s_waitcnt lgkmcnt(0)
	v_mfma_f32_16x16x32_bf16 v[60:63], v[158:161], v[198:201], v[60:63]
	v_mfma_f32_16x16x32_bf16 v[56:59], v[190:193], v[198:201], v[56:59]
	v_mfma_f32_16x16x32_bf16 v[52:55], v[158:161], v[206:209], v[52:55]
	v_mfma_f32_16x16x32_bf16 v[48:51], v[190:193], v[206:209], v[48:51]
	v_mfma_f32_16x16x32_bf16 v[44:47], v[158:161], v[214:217], v[44:47]
	v_mfma_f32_16x16x32_bf16 v[40:43], v[190:193], v[214:217], v[40:43]
	v_mfma_f32_16x16x32_bf16 v[36:39], v[158:161], v[222:225], v[36:39]
	v_mfma_f32_16x16x32_bf16 v[32:35], v[190:193], v[222:225], v[32:35]
	v_mfma_f32_16x16x32_bf16 v[60:63], v[186:189], v[202:205], v[60:63]
	v_mfma_f32_16x16x32_bf16 v[56:59], v[194:197], v[202:205], v[56:59]
	v_mfma_f32_16x16x32_bf16 v[52:55], v[186:189], v[210:213], v[52:55]
	v_mfma_f32_16x16x32_bf16 v[48:51], v[194:197], v[210:213], v[48:51]
	v_mfma_f32_16x16x32_bf16 v[44:47], v[186:189], v[218:221], v[44:47]
	v_mfma_f32_16x16x32_bf16 v[40:43], v[194:197], v[218:221], v[40:43]
	v_mfma_f32_16x16x32_bf16 v[36:39], v[186:189], v[226:229], v[36:39]
	v_mfma_f32_16x16x32_bf16 v[32:35], v[194:197], v[226:229], v[32:35]
	s_barrier
	s_add_u32 s88, s92, s88
	s_addc_u32 s89, s93, s89
	s_add_i32 s65, vcc_lo, s9
	s_mov_b32 m0, s65
	v_lshl_add_u64 v[160:161], s[88:89], 0, v[136:137]
	global_load_lds_dwordx4 v136, s[88:89]
	s_add_i32 m0, s65, 0x2000
	v_lshl_add_u64 v[138:139], s[88:89], 0, v[156:157]
	global_load_lds_dwordx4 v156, s[88:89]
	s_waitcnt vmcnt(6)
	s_barrier
; #define PG8_STAGE(bufoff, gbase, v0, v1) do { \
;         __builtin_amdgcn_global_load_lds((const unsigned*)((const char*)(gbase) + (v0)), (LAS unsigned*)(lds + (bufoff) + ldsw), 16, 0, 0); \
;         __builtin_amdgcn_global_load_lds((const unsigned*)((const char*)(gbase) + (v1)), (LAS unsigned*)(lds + (bufoff) + ldsw + 8192), 16, 0, 0); } while (0)
; #define PG8_LDA(dst, b, h) do { _Pragma("unroll") for (int m = 0; m < 4; ++m) _Pragma("unroll") for (int k = 0; k < 2; ++k) dst[m][k] = *(const LAS bf16x8*)(lds + PG8_SA(b, h) + aoff + m * 2048 + k * 1024); } while (0)
; #define PG8_LDB(dst, b, h) do { _Pragma("unroll") for (int n = 0; n < 2; ++n) _Pragma("unroll") for (int k = 0; k < 2; ++k) dst[n][k] = *(const LAS bf16x8*)(lds + PG8_SB(b, h) + boff + n * 2048 + k * 1024); } while (0)
; #define PG8_MMA(ai, bj, At, Bt) do { __builtin_amdgcn_s_setprio(1); _Pragma("unroll") for (int m = 0; m < 4; ++m) _Pragma("unroll") for (int n = 0; n < 2; ++n) _Pragma("unroll") for (int k = 0; k < 2; ++k) \
;         acc[ai][bj][m][n] = __builtin_amdgcn_mfma_f32_16x16x32_bf16(Bt[n][k], At[m][k], acc[ai][bj][m][n], 0, 0, 0); __builtin_amdgcn_s_setprio(0); } while (0)
; #define PG8_WAIT_V(n) asm volatile("s_waitcnt vmcnt(" #n ")" ::: "memory")
; #define PG8_WAIT_L(n) asm volatile("s_waitcnt lgkmcnt(" #n ")" ::: "memory")
; #define PG8_BAR __builtin_amdgcn_s_barrier()
; #define PG8_SCHED __builtin_amdgcn_sched_barrier(0)
; template <class Epi, class Sched>
; __device__ __forceinline__ void gemm_phase(LAS unsigned char* lds, const Sched& S, const Epi& E) {
;     ...
;             PG8_WAIT_V(6); PG8_BAR; PG8_MMA(1, 1, At, B1); PG8_BAR;
;             PG8_LDB(B0, 1, 0); PG8_SCHED; PG8_LDA(At, 1, 0); PG8_STAGE(PG8_SA(0, 1), a2 + xhA, xA0, xA1);
;             PG8_WAIT_L(8); PG8_BAR; PG8_WAIT_L(0); PG8_MMA(0, 0, At, B0); PG8_BAR; PG8_SCHED;
;             PG8_LDB(B1, 1, 1); PG8_STAGE(PG8_SB(1, 0), b3, xB0, xB1);
;             PG8_BAR; PG8_WAIT_L(0); PG8_MMA(0, 1, At, B1); PG8_BAR;
;             PG8_LDA(At, 1, 1); PG8_STAGE(PG8_SA(1, 0), a3, xA0, xA1);
;             PG8_BAR; PG8_WAIT_L(0); PG8_MMA(1, 0, At, B0); PG8_BAR; PG8_SCHED;
	v_mfma_f32_16x16x32_bf16 v[28:31], v[230:233], v[198:201], v[28:31]
	v_mfma_f32_16x16x32_bf16 v[24:27], v[238:241], v[198:201], v[24:27]
	v_mfma_f32_16x16x32_bf16 v[20:23], v[230:233], v[206:209], v[20:23]
	v_mfma_f32_16x16x32_bf16 v[16:19], v[238:241], v[206:209], v[16:19]
	v_mfma_f32_16x16x32_bf16 v[12:15], v[230:233], v[214:217], v[12:15]
	v_mfma_f32_16x16x32_bf16 v[8:11], v[238:241], v[214:217], v[8:11]
	v_mfma_f32_16x16x32_bf16 v[4:7], v[230:233], v[222:225], v[4:7]
	v_mfma_f32_16x16x32_bf16 v[0:3], v[238:241], v[222:225], v[0:3]
	v_mfma_f32_16x16x32_bf16 v[28:31], v[234:237], v[202:205], v[28:31]
	v_mfma_f32_16x16x32_bf16 v[24:27], v[242:245], v[202:205], v[24:27]
	v_mfma_f32_16x16x32_bf16 v[20:23], v[234:237], v[210:213], v[20:23]
	v_mfma_f32_16x16x32_bf16 v[16:19], v[242:245], v[210:213], v[16:19]
	v_mfma_f32_16x16x32_bf16 v[12:15], v[234:237], v[218:221], v[12:15]
	v_mfma_f32_16x16x32_bf16 v[8:11], v[242:245], v[218:221], v[8:11]
	v_mfma_f32_16x16x32_bf16 v[4:7], v[234:237], v[226:229], v[4:7]
	v_mfma_f32_16x16x32_bf16 v[0:3], v[242:245], v[226:229], v[0:3]
	s_add_i32 s65, 0, 0x18000
	v_add_u32_e32 v136, s65, v184
	s_barrier
	ds_read_b128 v[156:159], v136
	ds_read_b128 v[186:189], v136 offset:1024
	ds_read_b128 v[190:193], v136 offset:2048
	ds_read_b128 v[194:197], v136 offset:3072
	s_add_u32 s54, s54, s82
	s_addc_u32 s55, s55, s83
	s_mov_b32 m0, s51
	v_lshl_add_u64 v[154:155], s[54:55], 0, v[154:155]
	ds_read_b128 v[198:201], v185 offset:32768
	ds_read_b128 v[202:205], v185 offset:33792
	ds_read_b128 v[206:209], v185 offset:34816
	ds_read_b128 v[210:213], v185 offset:35840
	ds_read_b128 v[214:217], v185 offset:36864
	ds_read_b128 v[218:221], v185 offset:37888
	ds_read_b128 v[222:225], v185 offset:38912
	ds_read_b128 v[226:229], v185 offset:39936
	global_load_lds_dwordx4 v[154:155], off
	v_lshl_add_u64 v[152:153], s[54:55], 0, v[152:153]
	s_mov_b32 m0, s8
	s_nop 0
	global_load_lds_dwordx4 v[152:153], off
	s_waitcnt lgkmcnt(8)
	s_barrier
	s_waitcnt lgkmcnt(0)
	v_mfma_f32_16x16x32_bf16 v[124:127], v[156:159], v[198:201], v[124:127]
	v_mfma_f32_16x16x32_bf16 v[120:123], v[190:193], v[198:201], v[120:123]
	v_mfma_f32_16x16x32_bf16 v[116:119], v[156:159], v[206:209], v[116:119]
	v_mfma_f32_16x16x32_bf16 v[112:115], v[190:193], v[206:209], v[112:115]
	v_mfma_f32_16x16x32_bf16 v[108:111], v[156:159], v[214:217], v[108:111]
	v_mfma_f32_16x16x32_bf16 v[104:107], v[190:193], v[214:217], v[104:107]
	v_mfma_f32_16x16x32_bf16 v[100:103], v[156:159], v[222:225], v[100:103]
	v_mfma_f32_16x16x32_bf16 v[96:99], v[190:193], v[222:225], v[96:99]
	v_mfma_f32_16x16x32_bf16 v[124:127], v[186:189], v[202:205], v[124:127]
	v_mfma_f32_16x16x32_bf16 v[120:123], v[194:197], v[202:205], v[120:123]
	v_mfma_f32_16x16x32_bf16 v[116:119], v[186:189], v[210:213], v[116:119]
	v_mfma_f32_16x16x32_bf16 v[112:115], v[194:197], v[210:213], v[112:115]
	v_mfma_f32_16x16x32_bf16 v[108:111], v[186:189], v[218:221], v[108:111]
	v_mfma_f32_16x16x32_bf16 v[104:107], v[194:197], v[218:221], v[104:107]
	v_mfma_f32_16x16x32_bf16 v[100:103], v[186:189], v[226:229], v[100:103]
	v_mfma_f32_16x16x32_bf16 v[96:99], v[194:197], v[226:229], v[96:99]
	s_barrier
	s_add_i32 s54, 0, 0x1c000
	s_add_i32 s55, s65, s9
	v_add_u32_e32 v136, s54, v184
	v_lshl_add_u64 v[242:243], v[246:247], 0, s[44:45]
	s_mov_b32 m0, s55
	ds_read_b128 v[152:155], v136
	ds_read_b128 v[230:233], v136 offset:1024
	ds_read_b128 v[234:237], v136 offset:2048
	ds_read_b128 v[238:241], v136 offset:3072
	global_load_lds_dwordx4 v[242:243], off
	v_lshl_add_u64 v[242:243], v[248:249], 0, s[44:45]
	s_add_i32 m0, s55, 0x2000
	s_nop 0
	global_load_lds_dwordx4 v[242:243], off
	s_barrier
	s_waitcnt lgkmcnt(0)
	v_mfma_f32_16x16x32_bf16 v[92:95], v[152:155], v[198:201], v[92:95]
	v_mfma_f32_16x16x32_bf16 v[88:91], v[234:237], v[198:201], v[88:91]
	v_mfma_f32_16x16x32_bf16 v[84:87], v[152:155], v[206:209], v[84:87]
	v_mfma_f32_16x16x32_bf16 v[80:83], v[234:237], v[206:209], v[80:83]
	v_mfma_f32_16x16x32_bf16 v[76:79], v[152:155], v[214:217], v[76:79]
	v_mfma_f32_16x16x32_bf16 v[72:75], v[234:237], v[214:217], v[72:75]
	v_mfma_f32_16x16x32_bf16 v[68:71], v[152:155], v[222:225], v[68:71]
	v_mfma_f32_16x16x32_bf16 v[64:67], v[234:237], v[222:225], v[64:67]
	v_mfma_f32_16x16x32_bf16 v[92:95], v[230:233], v[202:205], v[92:95]
	v_mfma_f32_16x16x32_bf16 v[88:91], v[238:241], v[202:205], v[88:91]
	v_mfma_f32_16x16x32_bf16 v[84:87], v[230:233], v[210:213], v[84:87]
	v_mfma_f32_16x16x32_bf16 v[80:83], v[238:241], v[210:213], v[80:83]
	v_mfma_f32_16x16x32_bf16 v[76:79], v[230:233], v[218:221], v[76:79]
	v_mfma_f32_16x16x32_bf16 v[72:75], v[238:241], v[218:221], v[72:75]
	v_mfma_f32_16x16x32_bf16 v[68:71], v[230:233], v[226:229], v[68:71]
	v_mfma_f32_16x16x32_bf16 v[64:67], v[238:241], v[226:229], v[64:67]
	s_mov_b32 m0, s21
	v_lshl_add_u64 v[242:243], v[250:251], 0, s[44:45]
	s_barrier
; #define PG8_STAGE(bufoff, gbase, v0, v1) do { \
;         __builtin_amdgcn_global_load_lds((const unsigned*)((const char*)(gbase) + (v0)), (LAS unsigned*)(lds + (bufoff) + ldsw), 16, 0, 0); \
;         __builtin_amdgcn_global_load_lds((const unsigned*)((const char*)(gbase) + (v1)), (LAS unsigned*)(lds + (bufoff) + ldsw + 8192), 16, 0, 0); } while (0)
; #define PG8_LDA(dst, b, h) do { _Pragma("unroll") for (int m = 0; m < 4; ++m) _Pragma("unroll") for (int k = 0; k < 2; ++k) dst[m][k] = *(const LAS bf16x8*)(lds + PG8_SA(b, h) + aoff + m * 2048 + k * 1024); } while (0)
; #define PG8_MMA(ai, bj, At, Bt) do { __builtin_amdgcn_s_setprio(1); _Pragma("unroll") for (int m = 0; m < 4; ++m) _Pragma("unroll") for (int n = 0; n < 2; ++n) _Pragma("unroll") for (int k = 0; k < 2; ++k) \
;         acc[ai][bj][m][n] = __builtin_amdgcn_mfma_f32_16x16x32_bf16(Bt[n][k], At[m][k], acc[ai][bj][m][n], 0, 0, 0); __builtin_amdgcn_s_setprio(0); } while (0)
; #define PG8_WAIT_V(n) asm volatile("s_waitcnt vmcnt(" #n ")" ::: "memory")
; #define PG8_WAIT_L(n) asm volatile("s_waitcnt lgkmcnt(" #n ")" ::: "memory")
; #define PG8_BAR __builtin_amdgcn_s_barrier()
; #define PG8_SCHED __builtin_amdgcn_sched_barrier(0)
; template <class Epi, class Sched>
; __device__ __forceinline__ void gemm_phase(LAS unsigned char* lds, const Sched& S, const Epi& E) {
;     ...
;         for (int t = 0; t < nt; t += 2) {
;             const bool last = (t == nt - 2);
;             const char* a1 = cA + (size_t)(t + 1) * kstep;
;             const char* a2 = last ? nA : cA + (size_t)(t + 2) * kstep; const char* b2 = last ? nB : cB + (size_t)(t + 2) * kstep;
;             const char* a3 = a2 + kstep; const char* b3 = b2 + kstep;
;             const unsigned xA0 = last ? nvA0 : vA0, xA1 = last ? nvA1 : vA1, xB0 = last ? nvB0 : vB0, xB1 = last ? nvB1 : vB1;
;             const size_t xhA = last ? nhA : hA, xhB = last ? nhB : hB;
;     ...
;             PG8_LDA(At, 1, 1); PG8_STAGE(PG8_SA(1, 0), a3, xA0, xA1);
;             PG8_BAR; PG8_WAIT_L(0); PG8_MMA(1, 0, At, B0); PG8_BAR; PG8_SCHED;
;             PG8_STAGE(PG8_SB(1, 1), b3 + xhB, xB0, xB1);
;             PG8_WAIT_V(6); PG8_BAR; PG8_MMA(1, 1, At, B1); PG8_BAR;
;         }
	ds_read_b128 v[198:201], v185 offset:49152
	ds_read_b128 v[202:205], v185 offset:50176
	ds_read_b128 v[206:209], v185 offset:51200
	ds_read_b128 v[210:213], v185 offset:52224
	ds_read_b128 v[214:217], v185 offset:53248
	ds_read_b128 v[218:221], v185 offset:54272
	ds_read_b128 v[222:225], v185 offset:55296
	ds_read_b128 v[226:229], v185 offset:56320
	global_load_lds_dwordx4 v[242:243], off
	v_lshl_add_u64 v[140:141], v[140:141], 0, s[44:45]
	s_mov_b32 m0, s24
	s_nop 0
	global_load_lds_dwordx4 v[140:141], off
	s_barrier
	s_waitcnt lgkmcnt(0)
	v_mfma_f32_16x16x32_bf16 v[60:63], v[156:159], v[198:201], v[60:63]
	v_mfma_f32_16x16x32_bf16 v[56:59], v[190:193], v[198:201], v[56:59]
	v_mfma_f32_16x16x32_bf16 v[52:55], v[156:159], v[206:209], v[52:55]
	v_mfma_f32_16x16x32_bf16 v[48:51], v[190:193], v[206:209], v[48:51]
	v_mfma_f32_16x16x32_bf16 v[44:47], v[156:159], v[214:217], v[44:47]
	v_mfma_f32_16x16x32_bf16 v[40:43], v[190:193], v[214:217], v[40:43]
	v_mfma_f32_16x16x32_bf16 v[36:39], v[156:159], v[222:225], v[36:39]
	v_mfma_f32_16x16x32_bf16 v[32:35], v[190:193], v[222:225], v[32:35]
	v_mfma_f32_16x16x32_bf16 v[60:63], v[186:189], v[202:205], v[60:63]
	v_mfma_f32_16x16x32_bf16 v[56:59], v[194:197], v[202:205], v[56:59]
	v_mfma_f32_16x16x32_bf16 v[52:55], v[186:189], v[210:213], v[52:55]
	v_mfma_f32_16x16x32_bf16 v[48:51], v[194:197], v[210:213], v[48:51]
	v_mfma_f32_16x16x32_bf16 v[44:47], v[186:189], v[218:221], v[44:47]
	v_mfma_f32_16x16x32_bf16 v[40:43], v[194:197], v[218:221], v[40:43]
	v_mfma_f32_16x16x32_bf16 v[36:39], v[186:189], v[226:229], v[36:39]
	v_mfma_f32_16x16x32_bf16 v[32:35], v[194:197], v[226:229], v[32:35]
	s_barrier
	s_add_i32 s54, s54, s9
	v_lshl_add_u64 v[140:141], v[160:161], 0, s[44:45]
	s_mov_b32 m0, s54
	v_lshl_add_u64 v[138:139], v[138:139], 0, s[44:45]
	global_load_lds_dwordx4 v[140:141], off
	s_add_i32 m0, s54, 0x2000
	s_nop 0
	global_load_lds_dwordx4 v[138:139], off
	s_waitcnt vmcnt(6)
	s_barrier
	v_mfma_f32_16x16x32_bf16 v[28:31], v[152:155], v[198:201], v[28:31]
	v_mfma_f32_16x16x32_bf16 v[24:27], v[234:237], v[198:201], v[24:27]
	v_mfma_f32_16x16x32_bf16 v[20:23], v[152:155], v[206:209], v[20:23]
	v_mfma_f32_16x16x32_bf16 v[16:19], v[234:237], v[206:209], v[16:19]
	v_mfma_f32_16x16x32_bf16 v[12:15], v[152:155], v[214:217], v[12:15]
	v_mfma_f32_16x16x32_bf16 v[8:11], v[234:237], v[214:217], v[8:11]
	v_mfma_f32_16x16x32_bf16 v[4:7], v[152:155], v[222:225], v[4:7]
	v_mfma_f32_16x16x32_bf16 v[0:3], v[234:237], v[222:225], v[0:3]
	v_mfma_f32_16x16x32_bf16 v[28:31], v[230:233], v[202:205], v[28:31]
	v_mfma_f32_16x16x32_bf16 v[24:27], v[238:241], v[202:205], v[24:27]
	v_mfma_f32_16x16x32_bf16 v[20:23], v[230:233], v[210:213], v[20:23]
	v_mfma_f32_16x16x32_bf16 v[16:19], v[238:241], v[210:213], v[16:19]
	v_mfma_f32_16x16x32_bf16 v[12:15], v[230:233], v[218:221], v[12:15]
	v_mfma_f32_16x16x32_bf16 v[8:11], v[238:241], v[218:221], v[8:11]
	v_mfma_f32_16x16x32_bf16 v[4:7], v[230:233], v[226:229], v[4:7]
	v_mfma_f32_16x16x32_bf16 v[0:3], v[238:241], v[226:229], v[0:3]
	s_add_u32 s34, s34, 0x100
	s_addc_u32 s35, s35, 0
	s_add_u32 s70, s70, 0x100
	s_addc_u32 s71, s71, 0
	s_cmp_ge_i32 s49, s36
	s_cbranch_scc1 .Lrot_exit_1
	s_cmp_eq_u32 s39, s49
	s_cselect_b64 s[54:55], -1, 0
	s_and_b64 vcc, exec, s[54:55]
	v_mov_b64_e32 v[152:153], v[144:145]
	v_mov_b64_e32 v[154:155], v[142:143]
	s_mov_b64 s[88:89], s[68:69]
	s_mov_b64 s[82:83], s[66:67]
	v_mov_b32_e32 v156, v148
	v_mov_b32_e32 v136, v146
	s_mov_b64 s[92:93], s[42:43]
	s_cbranch_vccnz .Lrot_join_1
	v_mov_b64_e32 v[152:153], v[128:129]
	v_mov_b64_e32 v[154:155], v[132:133]
	s_mov_b64 s[88:89], s[12:13]
	s_mov_b64 s[82:83], s[14:15]
	v_mov_b32_e32 v156, v130
	v_mov_b32_e32 v136, v131
	s_mov_b64 s[92:93], s[70:71]
.Lrot_join_1:
	s_add_i32 s49, s49, 2
	s_add_u32 s65, s34, 0x80
	s_addc_u32 vcc_lo, s35, 0
	s_and_b64 s[54:55], exec, s[54:55]
	s_cselect_b32 s55, s41, vcc_lo
	s_cselect_b32 s54, s40, s65
	s_add_i32 s65, 0, 0x10000
	v_add_u32_e32 v138, s65, v184
	s_barrier
	s_branch .Lrot_body_1

; #define PG8_STAGE(bufoff, gbase, v0, v1) do { \
;         __builtin_amdgcn_global_load_lds((const unsigned*)((const char*)(gbase) + (v0)), (LAS unsigned*)(lds + (bufoff) + ldsw), 16, 0, 0); \
;         __builtin_amdgcn_global_load_lds((const unsigned*)((const char*)(gbase) + (v1)), (LAS unsigned*)(lds + (bufoff) + ldsw + 8192), 16, 0, 0); } while (0)
; #define PG8_LDA(dst, b, h) do { _Pragma("unroll") for (int m = 0; m < 4; ++m) _Pragma("unroll") for (int k = 0; k < 2; ++k) dst[m][k] = *(const LAS bf16x8*)(lds + PG8_SA(b, h) + aoff + m * 2048 + k * 1024); } while (0)
; #define PG8_LDB(dst, b, h) do { _Pragma("unroll") for (int n = 0; n < 2; ++n) _Pragma("unroll") for (int k = 0; k < 2; ++k) dst[n][k] = *(const LAS bf16x8*)(lds + PG8_SB(b, h) + boff + n * 2048 + k * 1024); } while (0)
; #define PG8_MMA(ai, bj, At, Bt) do { __builtin_amdgcn_s_setprio(1); _Pragma("unroll") for (int m = 0; m < 4; ++m) _Pragma("unroll") for (int n = 0; n < 2; ++n) _Pragma("unroll") for (int k = 0; k < 2; ++k) \
;         acc[ai][bj][m][n] = __builtin_amdgcn_mfma_f32_16x16x32_bf16(Bt[n][k], At[m][k], acc[ai][bj][m][n], 0, 0, 0); __builtin_amdgcn_s_setprio(0); } while (0)
; #define PG8_WAIT_V(n) asm volatile("s_waitcnt vmcnt(" #n ")" ::: "memory")
; #define PG8_WAIT_L(n) asm volatile("s_waitcnt lgkmcnt(" #n ")" ::: "memory")
; #define PG8_BAR __builtin_amdgcn_s_barrier()
; #define PG8_SCHED __builtin_amdgcn_sched_barrier(0)
; template <class Epi, class Sched>
; __device__ __forceinline__ void gemm_phase(LAS unsigned char* lds, const Sched& S, const Epi& E) {
;     ...
;             PG8_LDB(B0, 0, 0); PG8_SCHED; PG8_LDA(At, 0, 0); PG8_STAGE(PG8_SA(1, 1), a1 + hA, vA0, vA1);
;             PG8_WAIT_L(8); PG8_BAR; PG8_WAIT_L(0); PG8_MMA(0, 0, At, B0); PG8_BAR; PG8_SCHED;
;             PG8_LDB(B1, 0, 1); PG8_STAGE(PG8_SB(0, 0), b2, xB0, xB1);
;             PG8_BAR; PG8_WAIT_L(0); PG8_MMA(0, 1, At, B1); PG8_BAR;
;             PG8_LDA(At, 0, 1); PG8_STAGE(PG8_SA(0, 0), a2, xA0, xA1);
;             PG8_BAR; PG8_WAIT_L(0); PG8_MMA(1, 0, At, B0); PG8_BAR; PG8_SCHED;
;             PG8_STAGE(PG8_SB(0, 1), b2 + xhB, xB0, xB1);
;             PG8_WAIT_V(6); PG8_BAR; PG8_MMA(1, 1, At, B1); PG8_BAR;
.Lrot_body_2:
	ds_read_b128 v[150:153], v138
	ds_read_b128 v[154:157], v138 offset:1024
	ds_read_b128 v[158:161], v138 offset:2048
	ds_read_b128 v[182:185], v138 offset:3072
	v_lshl_add_u64 v[138:139], s[34:35], 0, v[136:137]
	s_add_i32 m0, s50, 0xc000
	ds_read_b128 v[186:189], v148
	ds_read_b128 v[190:193], v148 offset:1024
	ds_read_b128 v[194:197], v148 offset:2048
	ds_read_b128 v[198:201], v148 offset:3072
	ds_read_b128 v[202:205], v148 offset:4096
	ds_read_b128 v[206:209], v148 offset:5120
	ds_read_b128 v[210:213], v148 offset:6144
	ds_read_b128 v[214:217], v148 offset:7168
	global_load_lds_dwordx4 v[138:139], off
	v_lshl_add_u64 v[138:139], s[34:35], 0, v[132:133]
	s_add_i32 m0, s50, 0xe000
	s_nop 0
	global_load_lds_dwordx4 v[138:139], off
	s_waitcnt lgkmcnt(8)
	s_barrier
	s_waitcnt lgkmcnt(0)
	v_mfma_f32_16x16x32_bf16 v[124:127], v[150:153], v[186:189], v[124:127]
	v_mfma_f32_16x16x32_bf16 v[120:123], v[158:161], v[186:189], v[120:123]
	v_mfma_f32_16x16x32_bf16 v[108:111], v[150:153], v[194:197], v[108:111]
	v_mfma_f32_16x16x32_bf16 v[104:107], v[158:161], v[194:197], v[104:107]
	v_mfma_f32_16x16x32_bf16 v[92:95], v[150:153], v[202:205], v[92:95]
	v_mfma_f32_16x16x32_bf16 v[88:91], v[158:161], v[202:205], v[88:91]
	v_mfma_f32_16x16x32_bf16 v[76:79], v[150:153], v[210:213], v[76:79]
	v_mfma_f32_16x16x32_bf16 v[72:75], v[158:161], v[210:213], v[72:75]
	v_mfma_f32_16x16x32_bf16 v[124:127], v[154:157], v[190:193], v[124:127]
	v_mfma_f32_16x16x32_bf16 v[120:123], v[182:185], v[190:193], v[120:123]
	v_mfma_f32_16x16x32_bf16 v[108:111], v[154:157], v[198:201], v[108:111]
	v_mfma_f32_16x16x32_bf16 v[104:107], v[182:185], v[198:201], v[104:107]
	v_mfma_f32_16x16x32_bf16 v[92:95], v[154:157], v[206:209], v[92:95]
	v_mfma_f32_16x16x32_bf16 v[88:91], v[182:185], v[206:209], v[88:91]
	v_mfma_f32_16x16x32_bf16 v[76:79], v[154:157], v[214:217], v[76:79]
	v_mfma_f32_16x16x32_bf16 v[72:75], v[182:185], v[214:217], v[72:75]
	s_barrier
	s_add_i32 s71, 0, 0x14000
	v_add_u32_e32 v138, s71, v147
	s_add_i32 s23, s23, s49
	ds_read_b128 v[218:221], v138
	ds_read_b128 v[222:225], v138 offset:1024
	ds_read_b128 v[226:229], v138 offset:2048
	ds_read_b128 v[230:233], v138 offset:3072
	v_lshl_add_u64 v[138:139], s[40:41], 0, v[142:143]
	s_mov_b32 m0, s23
	v_lshl_add_u64 v[140:141], s[40:41], 0, v[134:135]
	global_load_lds_dwordx4 v[138:139], off
	s_add_i32 m0, s23, 0x2000
	s_nop 0
	global_load_lds_dwordx4 v[140:141], off
	s_barrier
	s_waitcnt lgkmcnt(0)
	v_mfma_f32_16x16x32_bf16 v[116:119], v[218:221], v[186:189], v[116:119]
	v_mfma_f32_16x16x32_bf16 v[112:115], v[226:229], v[186:189], v[112:115]
	v_mfma_f32_16x16x32_bf16 v[100:103], v[218:221], v[194:197], v[100:103]
	v_mfma_f32_16x16x32_bf16 v[96:99], v[226:229], v[194:197], v[96:99]
	v_mfma_f32_16x16x32_bf16 v[84:87], v[218:221], v[202:205], v[84:87]
	v_mfma_f32_16x16x32_bf16 v[80:83], v[226:229], v[202:205], v[80:83]
	v_mfma_f32_16x16x32_bf16 v[68:71], v[218:221], v[210:213], v[68:71]
	v_mfma_f32_16x16x32_bf16 v[64:67], v[226:229], v[210:213], v[64:67]
	v_mfma_f32_16x16x32_bf16 v[116:119], v[222:225], v[190:193], v[116:119]
	v_mfma_f32_16x16x32_bf16 v[112:115], v[230:233], v[190:193], v[112:115]
	v_mfma_f32_16x16x32_bf16 v[100:103], v[222:225], v[198:201], v[100:103]
	v_mfma_f32_16x16x32_bf16 v[96:99], v[230:233], v[198:201], v[96:99]
	v_mfma_f32_16x16x32_bf16 v[84:87], v[222:225], v[206:209], v[84:87]
	v_mfma_f32_16x16x32_bf16 v[80:83], v[230:233], v[206:209], v[80:83]
	v_mfma_f32_16x16x32_bf16 v[68:71], v[222:225], v[214:217], v[68:71]
	v_mfma_f32_16x16x32_bf16 v[64:67], v[230:233], v[214:217], v[64:67]
	s_mov_b32 m0, s50
	v_lshl_add_u64 v[234:235], s[42:43], 0, v[142:143]
	s_barrier
	ds_read_b128 v[186:189], v148 offset:16384
	ds_read_b128 v[190:193], v148 offset:17408
	ds_read_b128 v[194:197], v148 offset:18432
	ds_read_b128 v[198:201], v148 offset:19456
	ds_read_b128 v[202:205], v148 offset:20480
	ds_read_b128 v[206:209], v148 offset:21504
	ds_read_b128 v[210:213], v148 offset:22528
	ds_read_b128 v[214:217], v148 offset:23552
	global_load_lds_dwordx4 v[234:235], off
	v_lshl_add_u64 v[236:237], s[42:43], 0, v[134:135]
	s_mov_b32 m0, s51
	s_nop 0
	global_load_lds_dwordx4 v[236:237], off
	s_barrier
	s_waitcnt lgkmcnt(0)
	v_mfma_f32_16x16x32_bf16 v[60:63], v[150:153], v[186:189], v[60:63]
	v_mfma_f32_16x16x32_bf16 v[56:59], v[158:161], v[186:189], v[56:59]
	v_mfma_f32_16x16x32_bf16 v[44:47], v[150:153], v[194:197], v[44:47]
	v_mfma_f32_16x16x32_bf16 v[40:43], v[158:161], v[194:197], v[40:43]
	v_mfma_f32_16x16x32_bf16 v[28:31], v[150:153], v[202:205], v[28:31]
	v_mfma_f32_16x16x32_bf16 v[24:27], v[158:161], v[202:205], v[24:27]
	v_mfma_f32_16x16x32_bf16 v[12:15], v[150:153], v[210:213], v[12:15]
	v_mfma_f32_16x16x32_bf16 v[8:11], v[158:161], v[210:213], v[8:11]
	v_mfma_f32_16x16x32_bf16 v[60:63], v[154:157], v[190:193], v[60:63]
	v_mfma_f32_16x16x32_bf16 v[56:59], v[182:185], v[190:193], v[56:59]
	v_mfma_f32_16x16x32_bf16 v[44:47], v[154:157], v[198:201], v[44:47]
	v_mfma_f32_16x16x32_bf16 v[40:43], v[182:185], v[198:201], v[40:43]
	v_mfma_f32_16x16x32_bf16 v[28:31], v[154:157], v[206:209], v[28:31]
	v_mfma_f32_16x16x32_bf16 v[24:27], v[182:185], v[206:209], v[24:27]
	v_mfma_f32_16x16x32_bf16 v[12:15], v[154:157], v[214:217], v[12:15]
	v_mfma_f32_16x16x32_bf16 v[8:11], v[182:185], v[214:217], v[8:11]
	s_barrier
	s_add_u32 s82, s40, 0x80000
	s_addc_u32 s83, s41, 0
	s_add_i32 s23, s71, s49
	v_lshl_add_u64 v[150:151], s[82:83], 0, v[142:143]
	s_mov_b32 m0, s23
	s_nop 0
	global_load_lds_dwordx4 v[150:151], off
	v_lshl_add_u64 v[150:151], s[82:83], 0, v[134:135]
	s_add_i32 m0, s23, 0x2000
	s_nop 0
	global_load_lds_dwordx4 v[150:151], off
	s_waitcnt vmcnt(6)
	s_barrier
; #define PG8_STAGE(bufoff, gbase, v0, v1) do { \
;         __builtin_amdgcn_global_load_lds((const unsigned*)((const char*)(gbase) + (v0)), (LAS unsigned*)(lds + (bufoff) + ldsw), 16, 0, 0); \
;         __builtin_amdgcn_global_load_lds((const unsigned*)((const char*)(gbase) + (v1)), (LAS unsigned*)(lds + (bufoff) + ldsw + 8192), 16, 0, 0); } while (0)
; #define PG8_LDA(dst, b, h) do { _Pragma("unroll") for (int m = 0; m < 4; ++m) _Pragma("unroll") for (int k = 0; k < 2; ++k) dst[m][k] = *(const LAS bf16x8*)(lds + PG8_SA(b, h) + aoff + m * 2048 + k * 1024); } while (0)
; #define PG8_LDB(dst, b, h) do { _Pragma("unroll") for (int n = 0; n < 2; ++n) _Pragma("unroll") for (int k = 0; k < 2; ++k) dst[n][k] = *(const LAS bf16x8*)(lds + PG8_SB(b, h) + boff + n * 2048 + k * 1024); } while (0)
; #define PG8_MMA(ai, bj, At, Bt) do { __builtin_amdgcn_s_setprio(1); _Pragma("unroll") for (int m = 0; m < 4; ++m) _Pragma("unroll") for (int n = 0; n < 2; ++n) _Pragma("unroll") for (int k = 0; k < 2; ++k) \
;         acc[ai][bj][m][n] = __builtin_amdgcn_mfma_f32_16x16x32_bf16(Bt[n][k], At[m][k], acc[ai][bj][m][n], 0, 0, 0); __builtin_amdgcn_s_setprio(0); } while (0)
; #define PG8_WAIT_V(n) asm volatile("s_waitcnt vmcnt(" #n ")" ::: "memory")
; #define PG8_WAIT_L(n) asm volatile("s_waitcnt lgkmcnt(" #n ")" ::: "memory")
; #define PG8_BAR __builtin_amdgcn_s_barrier()
; #define PG8_SCHED __builtin_amdgcn_sched_barrier(0)
; template <class Epi, class Sched>
; __device__ __forceinline__ void gemm_phase(LAS unsigned char* lds, const Sched& S, const Epi& E) {
;     ...
;             PG8_WAIT_V(6); PG8_BAR; PG8_MMA(1, 1, At, B1); PG8_BAR;
;             PG8_LDB(B0, 1, 0); PG8_SCHED; PG8_LDA(At, 1, 0); PG8_STAGE(PG8_SA(0, 1), a2 + xhA, xA0, xA1);
;             PG8_WAIT_L(8); PG8_BAR; PG8_WAIT_L(0); PG8_MMA(0, 0, At, B0); PG8_BAR; PG8_SCHED;
;             PG8_LDB(B1, 1, 1); PG8_STAGE(PG8_SB(1, 0), b3, xB0, xB1);
;             PG8_BAR; PG8_WAIT_L(0); PG8_MMA(0, 1, At, B1); PG8_BAR;
;             PG8_LDA(At, 1, 1); PG8_STAGE(PG8_SA(1, 0), a3, xA0, xA1);
;             PG8_BAR; PG8_WAIT_L(0); PG8_MMA(1, 0, At, B0); PG8_BAR; PG8_SCHED;
	v_mfma_f32_16x16x32_bf16 v[52:55], v[218:221], v[186:189], v[52:55]
	v_mfma_f32_16x16x32_bf16 v[48:51], v[226:229], v[186:189], v[48:51]
	v_mfma_f32_16x16x32_bf16 v[36:39], v[218:221], v[194:197], v[36:39]
	v_mfma_f32_16x16x32_bf16 v[32:35], v[226:229], v[194:197], v[32:35]
	v_mfma_f32_16x16x32_bf16 v[20:23], v[218:221], v[202:205], v[20:23]
	v_mfma_f32_16x16x32_bf16 v[16:19], v[226:229], v[202:205], v[16:19]
	v_mfma_f32_16x16x32_bf16 v[4:7], v[218:221], v[210:213], v[4:7]
	v_mfma_f32_16x16x32_bf16 v[0:3], v[226:229], v[210:213], v[0:3]
	v_mfma_f32_16x16x32_bf16 v[52:55], v[222:225], v[190:193], v[52:55]
	v_mfma_f32_16x16x32_bf16 v[48:51], v[230:233], v[190:193], v[48:51]
	v_mfma_f32_16x16x32_bf16 v[36:39], v[222:225], v[198:201], v[36:39]
	v_mfma_f32_16x16x32_bf16 v[32:35], v[230:233], v[198:201], v[32:35]
	v_mfma_f32_16x16x32_bf16 v[20:23], v[222:225], v[206:209], v[20:23]
	v_mfma_f32_16x16x32_bf16 v[16:19], v[230:233], v[206:209], v[16:19]
	v_mfma_f32_16x16x32_bf16 v[4:7], v[222:225], v[214:217], v[4:7]
	v_mfma_f32_16x16x32_bf16 v[0:3], v[230:233], v[214:217], v[0:3]
	s_add_i32 s23, 0, 0x18000
	v_add_u32_e32 v149, s23, v147
	s_barrier
	ds_read_b128 v[150:153], v149
	ds_read_b128 v[154:157], v149 offset:1024
	ds_read_b128 v[158:161], v149 offset:2048
	ds_read_b128 v[182:185], v149 offset:3072
	s_add_u32 s42, s42, 0x80000
	s_addc_u32 s43, s43, 0
	s_mov_b32 m0, s54
	v_lshl_add_u64 v[218:219], s[42:43], 0, v[142:143]
	ds_read_b128 v[186:189], v148 offset:32768
	ds_read_b128 v[190:193], v148 offset:33792
	ds_read_b128 v[194:197], v148 offset:34816
	ds_read_b128 v[198:201], v148 offset:35840
	ds_read_b128 v[202:205], v148 offset:36864
	ds_read_b128 v[206:209], v148 offset:37888
	ds_read_b128 v[210:213], v148 offset:38912
	ds_read_b128 v[214:217], v148 offset:39936
	global_load_lds_dwordx4 v[218:219], off
	v_lshl_add_u64 v[218:219], s[42:43], 0, v[134:135]
	s_mov_b32 m0, s55
	s_nop 0
	global_load_lds_dwordx4 v[218:219], off
	s_waitcnt lgkmcnt(8)
	s_barrier
	s_waitcnt lgkmcnt(0)
	v_mfma_f32_16x16x32_bf16 v[124:127], v[150:153], v[186:189], v[124:127]
	v_mfma_f32_16x16x32_bf16 v[120:123], v[158:161], v[186:189], v[120:123]
	v_mfma_f32_16x16x32_bf16 v[108:111], v[150:153], v[194:197], v[108:111]
	v_mfma_f32_16x16x32_bf16 v[104:107], v[158:161], v[194:197], v[104:107]
	v_mfma_f32_16x16x32_bf16 v[92:95], v[150:153], v[202:205], v[92:95]
	v_mfma_f32_16x16x32_bf16 v[88:91], v[158:161], v[202:205], v[88:91]
	v_mfma_f32_16x16x32_bf16 v[76:79], v[150:153], v[210:213], v[76:79]
	v_mfma_f32_16x16x32_bf16 v[72:75], v[158:161], v[210:213], v[72:75]
	v_mfma_f32_16x16x32_bf16 v[124:127], v[154:157], v[190:193], v[124:127]
	v_mfma_f32_16x16x32_bf16 v[120:123], v[182:185], v[190:193], v[120:123]
	v_mfma_f32_16x16x32_bf16 v[108:111], v[154:157], v[198:201], v[108:111]
	v_mfma_f32_16x16x32_bf16 v[104:107], v[182:185], v[198:201], v[104:107]
	v_mfma_f32_16x16x32_bf16 v[92:95], v[154:157], v[206:209], v[92:95]
	v_mfma_f32_16x16x32_bf16 v[88:91], v[182:185], v[206:209], v[88:91]
	v_mfma_f32_16x16x32_bf16 v[76:79], v[154:157], v[214:217], v[76:79]
	v_mfma_f32_16x16x32_bf16 v[72:75], v[182:185], v[214:217], v[72:75]
	s_barrier
	s_add_i32 s42, 0, 0x1c000
	s_add_i32 s23, s23, s49
	v_add_u32_e32 v149, s42, v147
	v_lshl_add_u64 v[138:139], v[138:139], 0, s[44:45]
	s_mov_b32 m0, s23
	ds_read_b128 v[218:221], v149
	ds_read_b128 v[222:225], v149 offset:1024
	ds_read_b128 v[226:229], v149 offset:2048
	ds_read_b128 v[230:233], v149 offset:3072
	global_load_lds_dwordx4 v[138:139], off
	v_lshl_add_u64 v[138:139], v[140:141], 0, s[44:45]
	s_add_i32 m0, s23, 0x2000
	s_nop 0
	global_load_lds_dwordx4 v[138:139], off
	s_barrier
	s_waitcnt lgkmcnt(0)
	v_mfma_f32_16x16x32_bf16 v[116:119], v[218:221], v[186:189], v[116:119]
	v_mfma_f32_16x16x32_bf16 v[112:115], v[226:229], v[186:189], v[112:115]
	v_mfma_f32_16x16x32_bf16 v[100:103], v[218:221], v[194:197], v[100:103]
	v_mfma_f32_16x16x32_bf16 v[96:99], v[226:229], v[194:197], v[96:99]
	v_mfma_f32_16x16x32_bf16 v[84:87], v[218:221], v[202:205], v[84:87]
	v_mfma_f32_16x16x32_bf16 v[80:83], v[226:229], v[202:205], v[80:83]
	v_mfma_f32_16x16x32_bf16 v[68:71], v[218:221], v[210:213], v[68:71]
	v_mfma_f32_16x16x32_bf16 v[64:67], v[226:229], v[210:213], v[64:67]
	v_mfma_f32_16x16x32_bf16 v[116:119], v[222:225], v[190:193], v[116:119]
	v_mfma_f32_16x16x32_bf16 v[112:115], v[230:233], v[190:193], v[112:115]
	v_mfma_f32_16x16x32_bf16 v[100:103], v[222:225], v[198:201], v[100:103]
	v_mfma_f32_16x16x32_bf16 v[96:99], v[230:233], v[198:201], v[96:99]
	v_mfma_f32_16x16x32_bf16 v[84:87], v[222:225], v[206:209], v[84:87]
	v_mfma_f32_16x16x32_bf16 v[80:83], v[230:233], v[206:209], v[80:83]
	v_mfma_f32_16x16x32_bf16 v[68:71], v[222:225], v[214:217], v[68:71]
	v_mfma_f32_16x16x32_bf16 v[64:67], v[230:233], v[214:217], v[64:67]
	s_mov_b32 m0, s66
	v_lshl_add_u64 v[138:139], v[234:235], 0, s[44:45]
	s_barrier
; #define PG8_STAGE(bufoff, gbase, v0, v1) do { \
;         __builtin_amdgcn_global_load_lds((const unsigned*)((const char*)(gbase) + (v0)), (LAS unsigned*)(lds + (bufoff) + ldsw), 16, 0, 0); \
;         __builtin_amdgcn_global_load_lds((const unsigned*)((const char*)(gbase) + (v1)), (LAS unsigned*)(lds + (bufoff) + ldsw + 8192), 16, 0, 0); } while (0)
; #define PG8_LDA(dst, b, h) do { _Pragma("unroll") for (int m = 0; m < 4; ++m) _Pragma("unroll") for (int k = 0; k < 2; ++k) dst[m][k] = *(const LAS bf16x8*)(lds + PG8_SA(b, h) + aoff + m * 2048 + k * 1024); } while (0)
; #define PG8_MMA(ai, bj, At, Bt) do { __builtin_amdgcn_s_setprio(1); _Pragma("unroll") for (int m = 0; m < 4; ++m) _Pragma("unroll") for (int n = 0; n < 2; ++n) _Pragma("unroll") for (int k = 0; k < 2; ++k) \
;         acc[ai][bj][m][n] = __builtin_amdgcn_mfma_f32_16x16x32_bf16(Bt[n][k], At[m][k], acc[ai][bj][m][n], 0, 0, 0); __builtin_amdgcn_s_setprio(0); } while (0)
; #define PG8_WAIT_V(n) asm volatile("s_waitcnt vmcnt(" #n ")" ::: "memory")
; #define PG8_WAIT_L(n) asm volatile("s_waitcnt lgkmcnt(" #n ")" ::: "memory")
; #define PG8_BAR __builtin_amdgcn_s_barrier()
; #define PG8_SCHED __builtin_amdgcn_sched_barrier(0)
; template <class Epi, class Sched>
; __device__ __forceinline__ void gemm_phase(LAS unsigned char* lds, const Sched& S, const Epi& E) {
;     ...
;         for (int t = 0; t < nt; t += 2) {
;             const bool last = (t == nt - 2);
;             const char* a1 = cA + (size_t)(t + 1) * kstep;
;             const char* a2 = last ? nA : cA + (size_t)(t + 2) * kstep; const char* b2 = last ? nB : cB + (size_t)(t + 2) * kstep;
;             const char* a3 = a2 + kstep; const char* b3 = b2 + kstep;
;             const unsigned xA0 = last ? nvA0 : vA0, xA1 = last ? nvA1 : vA1, xB0 = last ? nvB0 : vB0, xB1 = last ? nvB1 : vB1;
;             const size_t xhA = last ? nhA : hA, xhB = last ? nhB : hB;
;     ...
;             PG8_LDA(At, 1, 1); PG8_STAGE(PG8_SA(1, 0), a3, xA0, xA1);
;             PG8_BAR; PG8_WAIT_L(0); PG8_MMA(1, 0, At, B0); PG8_BAR; PG8_SCHED;
;             PG8_STAGE(PG8_SB(1, 1), b3 + xhB, xB0, xB1);
;             PG8_WAIT_V(6); PG8_BAR; PG8_MMA(1, 1, At, B1); PG8_BAR;
;         }
	ds_read_b128 v[186:189], v148 offset:49152
	ds_read_b128 v[190:193], v148 offset:50176
	ds_read_b128 v[194:197], v148 offset:51200
	ds_read_b128 v[198:201], v148 offset:52224
	ds_read_b128 v[202:205], v148 offset:53248
	ds_read_b128 v[206:209], v148 offset:54272
	ds_read_b128 v[210:213], v148 offset:55296
	ds_read_b128 v[214:217], v148 offset:56320
	global_load_lds_dwordx4 v[138:139], off
	v_lshl_add_u64 v[138:139], v[236:237], 0, s[44:45]
	s_mov_b32 m0, s67
	s_nop 0
	global_load_lds_dwordx4 v[138:139], off
	s_barrier
	s_waitcnt lgkmcnt(0)
	v_mfma_f32_16x16x32_bf16 v[60:63], v[150:153], v[186:189], v[60:63]
	v_mfma_f32_16x16x32_bf16 v[56:59], v[158:161], v[186:189], v[56:59]
	v_mfma_f32_16x16x32_bf16 v[44:47], v[150:153], v[194:197], v[44:47]
	v_mfma_f32_16x16x32_bf16 v[40:43], v[158:161], v[194:197], v[40:43]
	v_mfma_f32_16x16x32_bf16 v[28:31], v[150:153], v[202:205], v[28:31]
	v_mfma_f32_16x16x32_bf16 v[24:27], v[158:161], v[202:205], v[24:27]
	v_mfma_f32_16x16x32_bf16 v[12:15], v[150:153], v[210:213], v[12:15]
	v_mfma_f32_16x16x32_bf16 v[8:11], v[158:161], v[210:213], v[8:11]
	v_mfma_f32_16x16x32_bf16 v[60:63], v[154:157], v[190:193], v[60:63]
	v_mfma_f32_16x16x32_bf16 v[56:59], v[182:185], v[190:193], v[56:59]
	v_mfma_f32_16x16x32_bf16 v[44:47], v[154:157], v[198:201], v[44:47]
	v_mfma_f32_16x16x32_bf16 v[40:43], v[182:185], v[198:201], v[40:43]
	v_mfma_f32_16x16x32_bf16 v[28:31], v[154:157], v[206:209], v[28:31]
	v_mfma_f32_16x16x32_bf16 v[24:27], v[182:185], v[206:209], v[24:27]
	v_mfma_f32_16x16x32_bf16 v[12:15], v[154:157], v[214:217], v[12:15]
	v_mfma_f32_16x16x32_bf16 v[8:11], v[182:185], v[214:217], v[8:11]
	s_barrier
	s_add_u32 s40, s40, 0x80080
	s_addc_u32 s41, s41, 0
	s_add_i32 s23, s42, s49
	v_lshl_add_u64 v[138:139], s[40:41], 0, v[142:143]
	s_mov_b32 m0, s23
	v_lshl_add_u64 v[134:135], s[40:41], 0, v[134:135]
	global_load_lds_dwordx4 v[138:139], off
	s_add_i32 m0, s23, 0x2000
	s_nop 0
	global_load_lds_dwordx4 v[134:135], off
	s_waitcnt vmcnt(6)
	s_barrier
	v_mfma_f32_16x16x32_bf16 v[52:55], v[218:221], v[186:189], v[52:55]
	v_mfma_f32_16x16x32_bf16 v[48:51], v[226:229], v[186:189], v[48:51]
	v_mfma_f32_16x16x32_bf16 v[36:39], v[218:221], v[194:197], v[36:39]
	v_mfma_f32_16x16x32_bf16 v[32:35], v[226:229], v[194:197], v[32:35]
	v_mfma_f32_16x16x32_bf16 v[20:23], v[218:221], v[202:205], v[20:23]
	v_mfma_f32_16x16x32_bf16 v[16:19], v[226:229], v[202:205], v[16:19]
	v_mfma_f32_16x16x32_bf16 v[4:7], v[218:221], v[210:213], v[4:7]
	v_mfma_f32_16x16x32_bf16 v[0:3], v[226:229], v[210:213], v[0:3]
	v_mfma_f32_16x16x32_bf16 v[52:55], v[222:225], v[190:193], v[52:55]
	v_mfma_f32_16x16x32_bf16 v[48:51], v[230:233], v[190:193], v[48:51]
	v_mfma_f32_16x16x32_bf16 v[36:39], v[222:225], v[198:201], v[36:39]
	v_mfma_f32_16x16x32_bf16 v[32:35], v[230:233], v[198:201], v[32:35]
	v_mfma_f32_16x16x32_bf16 v[20:23], v[222:225], v[206:209], v[20:23]
	v_mfma_f32_16x16x32_bf16 v[16:19], v[230:233], v[206:209], v[16:19]
	v_mfma_f32_16x16x32_bf16 v[4:7], v[222:225], v[214:217], v[4:7]
	v_mfma_f32_16x16x32_bf16 v[0:3], v[230:233], v[214:217], v[0:3]
	s_add_i32 s21, s21, 2
	s_add_u32 s34, s34, 0x100
	s_addc_u32 s35, s35, 0
	s_add_u32 s38, s38, 0x100
	s_addc_u32 s39, s39, 0
	s_cmp_gt_u32 s21, 29
	s_cbranch_scc1 .Lrot_exit_2
	s_cmp_eq_u32 s21, 28
	s_cselect_b64 s[42:43], -1, 0
	s_and_b64 vcc, exec, s[42:43]
	v_mov_b64_e32 v[134:135], v[130:131]
	v_mov_b64_e32 v[142:143], v[128:129]
	s_mov_b64 s[40:41], s[26:27]
	s_cbranch_vccnz .Lrot_join_2
	v_mov_b64_e32 v[134:135], v[132:133]
	v_mov_b64_e32 v[142:143], v[136:137]
	s_mov_b64 s[40:41], s[38:39]
.Lrot_join_2:
	s_add_u32 s23, s34, 0xfff80080
	s_addc_u32 s71, s35, -1
	s_and_b64 s[42:43], exec, s[42:43]
	s_cselect_b32 s43, s25, s71
	s_cselect_b32 s42, s24, s23
	s_add_i32 s23, 0, 0x10000
	v_add_u32_e32 v138, s23, v147
	s_barrier
	s_branch .Lrot_body_2

; #define PG8_STAGE(bufoff, gbase, v0, v1) do { \
;         __builtin_amdgcn_global_load_lds((const unsigned*)((const char*)(gbase) + (v0)), (LAS unsigned*)(lds + (bufoff) + ldsw), 16, 0, 0); \
;         __builtin_amdgcn_global_load_lds((const unsigned*)((const char*)(gbase) + (v1)), (LAS unsigned*)(lds + (bufoff) + ldsw + 8192), 16, 0, 0); } while (0)
; #define PG8_LDA(dst, b, h) do { _Pragma("unroll") for (int m = 0; m < 4; ++m) _Pragma("unroll") for (int k = 0; k < 2; ++k) dst[m][k] = *(const LAS bf16x8*)(lds + PG8_SA(b, h) + aoff + m * 2048 + k * 1024); } while (0)
; #define PG8_LDB(dst, b, h) do { _Pragma("unroll") for (int n = 0; n < 2; ++n) _Pragma("unroll") for (int k = 0; k < 2; ++k) dst[n][k] = *(const LAS bf16x8*)(lds + PG8_SB(b, h) + boff + n * 2048 + k * 1024); } while (0)
; #define PG8_MMA(ai, bj, At, Bt) do { __builtin_amdgcn_s_setprio(1); _Pragma("unroll") for (int m = 0; m < 4; ++m) _Pragma("unroll") for (int n = 0; n < 2; ++n) _Pragma("unroll") for (int k = 0; k < 2; ++k) \
;         acc[ai][bj][m][n] = __builtin_amdgcn_mfma_f32_16x16x32_bf16(Bt[n][k], At[m][k], acc[ai][bj][m][n], 0, 0, 0); __builtin_amdgcn_s_setprio(0); } while (0)
; #define PG8_WAIT_V(n) asm volatile("s_waitcnt vmcnt(" #n ")" ::: "memory")
; #define PG8_WAIT_L(n) asm volatile("s_waitcnt lgkmcnt(" #n ")" ::: "memory")
; #define PG8_BAR __builtin_amdgcn_s_barrier()
; #define PG8_SCHED __builtin_amdgcn_sched_barrier(0)
; template <class Epi, class Sched>
; __device__ __forceinline__ void gemm_phase(LAS unsigned char* lds, const Sched& S, const Epi& E) {
;     ...
;             PG8_LDB(B0, 0, 0); PG8_SCHED; PG8_LDA(At, 0, 0); PG8_STAGE(PG8_SA(1, 1), a1 + hA, vA0, vA1);
;             PG8_WAIT_L(8); PG8_BAR; PG8_WAIT_L(0); PG8_MMA(0, 0, At, B0); PG8_BAR; PG8_SCHED;
;             PG8_LDB(B1, 0, 1); PG8_STAGE(PG8_SB(0, 0), b2, xB0, xB1);
;             PG8_BAR; PG8_WAIT_L(0); PG8_MMA(0, 1, At, B1); PG8_BAR;
;             PG8_LDA(At, 0, 1); PG8_STAGE(PG8_SA(0, 0), a2, xA0, xA1);
;             PG8_BAR; PG8_WAIT_L(0); PG8_MMA(1, 0, At, B0); PG8_BAR; PG8_SCHED;
;             PG8_STAGE(PG8_SB(0, 1), b2 + xhB, xB0, xB1);
;             PG8_WAIT_V(6); PG8_BAR; PG8_MMA(1, 1, At, B1); PG8_BAR;
.Lrot_body_3:
	ds_read_b128 v[158:161], v138
	ds_read_b128 v[182:185], v138 offset:1024
	ds_read_b128 v[186:189], v138 offset:2048
	ds_read_b128 v[190:193], v138 offset:3072
	v_lshl_add_u64 v[138:139], s[26:27], 0, v[132:133]
	s_add_i32 m0, s48, 0xc000
	ds_read_b128 v[194:197], v143
	ds_read_b128 v[198:201], v143 offset:1024
	ds_read_b128 v[202:205], v143 offset:2048
	ds_read_b128 v[206:209], v143 offset:3072
	ds_read_b128 v[210:213], v143 offset:4096
	ds_read_b128 v[214:217], v143 offset:5120
	ds_read_b128 v[218:221], v143 offset:6144
	ds_read_b128 v[222:225], v143 offset:7168
	global_load_lds_dwordx4 v[138:139], off
	v_lshl_add_u64 v[138:139], s[26:27], 0, v[134:135]
	s_add_i32 m0, s48, 0xe000
	s_nop 0
	global_load_lds_dwordx4 v[138:139], off
	s_waitcnt lgkmcnt(8)
	s_barrier
	s_waitcnt lgkmcnt(0)
	v_mfma_f32_16x16x32_bf16 v[124:127], v[158:161], v[194:197], v[124:127]
	v_mfma_f32_16x16x32_bf16 v[120:123], v[186:189], v[194:197], v[120:123]
	v_mfma_f32_16x16x32_bf16 v[112:115], v[158:161], v[202:205], v[112:115]
	v_mfma_f32_16x16x32_bf16 v[104:107], v[186:189], v[202:205], v[104:107]
	v_mfma_f32_16x16x32_bf16 v[96:99], v[158:161], v[210:213], v[96:99]
	v_mfma_f32_16x16x32_bf16 v[88:91], v[186:189], v[210:213], v[88:91]
	v_mfma_f32_16x16x32_bf16 v[80:83], v[158:161], v[218:221], v[80:83]
	v_mfma_f32_16x16x32_bf16 v[72:75], v[186:189], v[218:221], v[72:75]
	v_mfma_f32_16x16x32_bf16 v[124:127], v[182:185], v[198:201], v[124:127]
	v_mfma_f32_16x16x32_bf16 v[120:123], v[190:193], v[198:201], v[120:123]
	v_mfma_f32_16x16x32_bf16 v[112:115], v[182:185], v[206:209], v[112:115]
	v_mfma_f32_16x16x32_bf16 v[104:107], v[190:193], v[206:209], v[104:107]
	v_mfma_f32_16x16x32_bf16 v[96:99], v[182:185], v[214:217], v[96:99]
	v_mfma_f32_16x16x32_bf16 v[88:91], v[190:193], v[214:217], v[88:91]
	v_mfma_f32_16x16x32_bf16 v[80:83], v[182:185], v[222:225], v[80:83]
	v_mfma_f32_16x16x32_bf16 v[72:75], v[190:193], v[222:225], v[72:75]
	s_barrier
	s_add_i32 s69, 0, 0x14000
	s_add_i32 s21, s21, s43
	v_add_u32_e32 v138, s69, v155
	s_mov_b32 m0, s21
	ds_read_b128 v[226:229], v138
	ds_read_b128 v[230:233], v138 offset:1024
	ds_read_b128 v[234:237], v138 offset:2048
	ds_read_b128 v[238:241], v138 offset:3072
	global_load_lds_dwordx4 v136, s[38:39]
	s_add_i32 m0, s21, 0x2000
	v_mov_b32_e32 v147, v137
	global_load_lds_dwordx4 v146, s[38:39]
	v_lshl_add_u64 v[138:139], s[38:39], 0, v[136:137]
	v_lshl_add_u64 v[140:141], s[38:39], 0, v[146:147]
	s_barrier
	s_waitcnt lgkmcnt(0)
	v_mfma_f32_16x16x32_bf16 v[116:119], v[226:229], v[194:197], v[116:119]
	v_mfma_f32_16x16x32_bf16 v[108:111], v[234:237], v[194:197], v[108:111]
	v_mfma_f32_16x16x32_bf16 v[100:103], v[226:229], v[202:205], v[100:103]
	v_mfma_f32_16x16x32_bf16 v[92:95], v[234:237], v[202:205], v[92:95]
	v_mfma_f32_16x16x32_bf16 v[84:87], v[226:229], v[210:213], v[84:87]
	v_mfma_f32_16x16x32_bf16 v[76:79], v[234:237], v[210:213], v[76:79]
	v_mfma_f32_16x16x32_bf16 v[68:71], v[226:229], v[218:221], v[68:71]
	v_mfma_f32_16x16x32_bf16 v[64:67], v[234:237], v[218:221], v[64:67]
	v_mfma_f32_16x16x32_bf16 v[116:119], v[230:233], v[198:201], v[116:119]
	v_mfma_f32_16x16x32_bf16 v[108:111], v[238:241], v[198:201], v[108:111]
	v_mfma_f32_16x16x32_bf16 v[100:103], v[230:233], v[206:209], v[100:103]
	v_mfma_f32_16x16x32_bf16 v[92:95], v[238:241], v[206:209], v[92:95]
	v_mfma_f32_16x16x32_bf16 v[84:87], v[230:233], v[214:217], v[84:87]
	v_mfma_f32_16x16x32_bf16 v[76:79], v[238:241], v[214:217], v[76:79]
	v_mfma_f32_16x16x32_bf16 v[68:71], v[230:233], v[222:225], v[68:71]
	v_mfma_f32_16x16x32_bf16 v[64:67], v[238:241], v[222:225], v[64:67]
	s_mov_b32 m0, s48
	v_lshl_add_u64 v[242:243], s[40:41], 0, v[150:151]
	s_barrier
	ds_read_b128 v[194:197], v143 offset:16384
	ds_read_b128 v[198:201], v143 offset:17408
	ds_read_b128 v[202:205], v143 offset:18432
	ds_read_b128 v[206:209], v143 offset:19456
	ds_read_b128 v[210:213], v143 offset:20480
	ds_read_b128 v[214:217], v143 offset:21504
	ds_read_b128 v[218:221], v143 offset:22528
	ds_read_b128 v[222:225], v143 offset:23552
	global_load_lds_dwordx4 v[242:243], off
	v_lshl_add_u64 v[244:245], s[40:41], 0, v[148:149]
	s_mov_b32 m0, s49
	s_nop 0
	global_load_lds_dwordx4 v[244:245], off
	s_barrier
	s_waitcnt lgkmcnt(0)
	v_mfma_f32_16x16x32_bf16 v[60:63], v[158:161], v[194:197], v[60:63]
	v_mfma_f32_16x16x32_bf16 v[56:59], v[186:189], v[194:197], v[56:59]
	v_mfma_f32_16x16x32_bf16 v[44:47], v[158:161], v[202:205], v[44:47]
	v_mfma_f32_16x16x32_bf16 v[40:43], v[186:189], v[202:205], v[40:43]
	v_mfma_f32_16x16x32_bf16 v[28:31], v[158:161], v[210:213], v[28:31]
	v_mfma_f32_16x16x32_bf16 v[24:27], v[186:189], v[210:213], v[24:27]
	v_mfma_f32_16x16x32_bf16 v[12:15], v[158:161], v[218:221], v[12:15]
	v_mfma_f32_16x16x32_bf16 v[8:11], v[186:189], v[218:221], v[8:11]
	v_mfma_f32_16x16x32_bf16 v[60:63], v[182:185], v[198:201], v[60:63]
	v_mfma_f32_16x16x32_bf16 v[56:59], v[190:193], v[198:201], v[56:59]
	v_mfma_f32_16x16x32_bf16 v[44:47], v[182:185], v[206:209], v[44:47]
	v_mfma_f32_16x16x32_bf16 v[40:43], v[190:193], v[206:209], v[40:43]
	v_mfma_f32_16x16x32_bf16 v[28:31], v[182:185], v[214:217], v[28:31]
	v_mfma_f32_16x16x32_bf16 v[24:27], v[190:193], v[214:217], v[24:27]
	v_mfma_f32_16x16x32_bf16 v[12:15], v[182:185], v[222:225], v[12:15]
	v_mfma_f32_16x16x32_bf16 v[8:11], v[190:193], v[222:225], v[8:11]
	s_barrier
	s_add_u32 s70, s38, 0x80000
	s_addc_u32 s71, s39, 0
	s_add_i32 s21, s69, s43
	s_mov_b32 m0, s21
	s_nop 0
	global_load_lds_dwordx4 v136, s[70:71]
	s_add_i32 m0, s21, 0x2000
	s_nop 0
	global_load_lds_dwordx4 v146, s[70:71]
	s_waitcnt vmcnt(6)
	s_barrier
; #define PG8_STAGE(bufoff, gbase, v0, v1) do { \
;         __builtin_amdgcn_global_load_lds((const unsigned*)((const char*)(gbase) + (v0)), (LAS unsigned*)(lds + (bufoff) + ldsw), 16, 0, 0); \
;         __builtin_amdgcn_global_load_lds((const unsigned*)((const char*)(gbase) + (v1)), (LAS unsigned*)(lds + (bufoff) + ldsw + 8192), 16, 0, 0); } while (0)
; #define PG8_LDA(dst, b, h) do { _Pragma("unroll") for (int m = 0; m < 4; ++m) _Pragma("unroll") for (int k = 0; k < 2; ++k) dst[m][k] = *(const LAS bf16x8*)(lds + PG8_SA(b, h) + aoff + m * 2048 + k * 1024); } while (0)
; #define PG8_LDB(dst, b, h) do { _Pragma("unroll") for (int n = 0; n < 2; ++n) _Pragma("unroll") for (int k = 0; k < 2; ++k) dst[n][k] = *(const LAS bf16x8*)(lds + PG8_SB(b, h) + boff + n * 2048 + k * 1024); } while (0)
; #define PG8_MMA(ai, bj, At, Bt) do { __builtin_amdgcn_s_setprio(1); _Pragma("unroll") for (int m = 0; m < 4; ++m) _Pragma("unroll") for (int n = 0; n < 2; ++n) _Pragma("unroll") for (int k = 0; k < 2; ++k) \
;         acc[ai][bj][m][n] = __builtin_amdgcn_mfma_f32_16x16x32_bf16(Bt[n][k], At[m][k], acc[ai][bj][m][n], 0, 0, 0); __builtin_amdgcn_s_setprio(0); } while (0)
; #define PG8_WAIT_V(n) asm volatile("s_waitcnt vmcnt(" #n ")" ::: "memory")
; #define PG8_WAIT_L(n) asm volatile("s_waitcnt lgkmcnt(" #n ")" ::: "memory")
; #define PG8_BAR __builtin_amdgcn_s_barrier()
; #define PG8_SCHED __builtin_amdgcn_sched_barrier(0)
; template <class Epi, class Sched>
; __device__ __forceinline__ void gemm_phase(LAS unsigned char* lds, const Sched& S, const Epi& E) {
;     ...
;             PG8_WAIT_V(6); PG8_BAR; PG8_MMA(1, 1, At, B1); PG8_BAR;
;             PG8_LDB(B0, 1, 0); PG8_SCHED; PG8_LDA(At, 1, 0); PG8_STAGE(PG8_SA(0, 1), a2 + xhA, xA0, xA1);
;             PG8_WAIT_L(8); PG8_BAR; PG8_WAIT_L(0); PG8_MMA(0, 0, At, B0); PG8_BAR; PG8_SCHED;
;             PG8_LDB(B1, 1, 1); PG8_STAGE(PG8_SB(1, 0), b3, xB0, xB1);
;             PG8_BAR; PG8_WAIT_L(0); PG8_MMA(0, 1, At, B1); PG8_BAR;
;             PG8_LDA(At, 1, 1); PG8_STAGE(PG8_SA(1, 0), a3, xA0, xA1);
;             PG8_BAR; PG8_WAIT_L(0); PG8_MMA(1, 0, At, B0); PG8_BAR; PG8_SCHED;
	v_mfma_f32_16x16x32_bf16 v[52:55], v[226:229], v[194:197], v[52:55]
	v_mfma_f32_16x16x32_bf16 v[48:51], v[234:237], v[194:197], v[48:51]
	v_mfma_f32_16x16x32_bf16 v[36:39], v[226:229], v[202:205], v[36:39]
	v_mfma_f32_16x16x32_bf16 v[32:35], v[234:237], v[202:205], v[32:35]
	v_mfma_f32_16x16x32_bf16 v[20:23], v[226:229], v[210:213], v[20:23]
	v_mfma_f32_16x16x32_bf16 v[16:19], v[234:237], v[210:213], v[16:19]
	v_mfma_f32_16x16x32_bf16 v[4:7], v[226:229], v[218:221], v[4:7]
	v_mfma_f32_16x16x32_bf16 v[0:3], v[234:237], v[218:221], v[0:3]
	v_mfma_f32_16x16x32_bf16 v[52:55], v[230:233], v[198:201], v[52:55]
	v_mfma_f32_16x16x32_bf16 v[48:51], v[238:241], v[198:201], v[48:51]
	v_mfma_f32_16x16x32_bf16 v[36:39], v[230:233], v[206:209], v[36:39]
	v_mfma_f32_16x16x32_bf16 v[32:35], v[238:241], v[206:209], v[32:35]
	v_mfma_f32_16x16x32_bf16 v[20:23], v[230:233], v[214:217], v[20:23]
	v_mfma_f32_16x16x32_bf16 v[16:19], v[238:241], v[214:217], v[16:19]
	v_mfma_f32_16x16x32_bf16 v[4:7], v[230:233], v[222:225], v[4:7]
	v_mfma_f32_16x16x32_bf16 v[0:3], v[238:241], v[222:225], v[0:3]
	s_add_i32 s21, 0, 0x18000
	v_add_u32_e32 v147, s21, v155
	s_barrier
	ds_read_b128 v[158:161], v147
	ds_read_b128 v[182:185], v147 offset:1024
	ds_read_b128 v[186:189], v147 offset:2048
	ds_read_b128 v[190:193], v147 offset:3072
	s_add_u32 s40, s40, 0x80000
	s_addc_u32 s41, s41, 0
	s_mov_b32 m0, s50
	v_lshl_add_u64 v[150:151], s[40:41], 0, v[150:151]
	ds_read_b128 v[194:197], v143 offset:32768
	ds_read_b128 v[198:201], v143 offset:33792
	ds_read_b128 v[202:205], v143 offset:34816
	ds_read_b128 v[206:209], v143 offset:35840
	ds_read_b128 v[210:213], v143 offset:36864
	ds_read_b128 v[214:217], v143 offset:37888
	ds_read_b128 v[218:221], v143 offset:38912
	ds_read_b128 v[222:225], v143 offset:39936
	global_load_lds_dwordx4 v[150:151], off
	v_lshl_add_u64 v[148:149], s[40:41], 0, v[148:149]
	s_mov_b32 m0, s51
	s_nop 0
	global_load_lds_dwordx4 v[148:149], off
	s_waitcnt lgkmcnt(8)
	s_barrier
	s_waitcnt lgkmcnt(0)
	v_mfma_f32_16x16x32_bf16 v[124:127], v[158:161], v[194:197], v[124:127]
	v_mfma_f32_16x16x32_bf16 v[120:123], v[186:189], v[194:197], v[120:123]
	v_mfma_f32_16x16x32_bf16 v[112:115], v[158:161], v[202:205], v[112:115]
	v_mfma_f32_16x16x32_bf16 v[104:107], v[186:189], v[202:205], v[104:107]
	v_mfma_f32_16x16x32_bf16 v[96:99], v[158:161], v[210:213], v[96:99]
	v_mfma_f32_16x16x32_bf16 v[88:91], v[186:189], v[210:213], v[88:91]
	v_mfma_f32_16x16x32_bf16 v[80:83], v[158:161], v[218:221], v[80:83]
	v_mfma_f32_16x16x32_bf16 v[72:75], v[186:189], v[218:221], v[72:75]
	v_mfma_f32_16x16x32_bf16 v[124:127], v[182:185], v[198:201], v[124:127]
	v_mfma_f32_16x16x32_bf16 v[120:123], v[190:193], v[198:201], v[120:123]
	v_mfma_f32_16x16x32_bf16 v[112:115], v[182:185], v[206:209], v[112:115]
	v_mfma_f32_16x16x32_bf16 v[104:107], v[190:193], v[206:209], v[104:107]
	v_mfma_f32_16x16x32_bf16 v[96:99], v[182:185], v[214:217], v[96:99]
	v_mfma_f32_16x16x32_bf16 v[88:91], v[190:193], v[214:217], v[88:91]
	v_mfma_f32_16x16x32_bf16 v[80:83], v[182:185], v[222:225], v[80:83]
	v_mfma_f32_16x16x32_bf16 v[72:75], v[190:193], v[222:225], v[72:75]
	s_barrier
	s_add_i32 s40, 0, 0x1c000
	s_add_i32 s21, s21, s43
	v_add_u32_e32 v147, s40, v155
	v_lshl_add_u64 v[138:139], v[138:139], 0, s[44:45]
	s_mov_b32 m0, s21
	ds_read_b128 v[148:151], v147
	ds_read_b128 v[226:229], v147 offset:1024
	ds_read_b128 v[230:233], v147 offset:2048
	ds_read_b128 v[234:237], v147 offset:3072
	global_load_lds_dwordx4 v[138:139], off
	v_lshl_add_u64 v[138:139], v[140:141], 0, s[44:45]
	s_add_i32 m0, s21, 0x2000
	s_nop 0
	global_load_lds_dwordx4 v[138:139], off
	s_barrier
	s_waitcnt lgkmcnt(0)
	v_mfma_f32_16x16x32_bf16 v[116:119], v[148:151], v[194:197], v[116:119]
	v_mfma_f32_16x16x32_bf16 v[108:111], v[230:233], v[194:197], v[108:111]
	v_mfma_f32_16x16x32_bf16 v[100:103], v[148:151], v[202:205], v[100:103]
	v_mfma_f32_16x16x32_bf16 v[92:95], v[230:233], v[202:205], v[92:95]
	v_mfma_f32_16x16x32_bf16 v[84:87], v[148:151], v[210:213], v[84:87]
	v_mfma_f32_16x16x32_bf16 v[76:79], v[230:233], v[210:213], v[76:79]
	v_mfma_f32_16x16x32_bf16 v[68:71], v[148:151], v[218:221], v[68:71]
	v_mfma_f32_16x16x32_bf16 v[64:67], v[230:233], v[218:221], v[64:67]
	v_mfma_f32_16x16x32_bf16 v[116:119], v[226:229], v[198:201], v[116:119]
	v_mfma_f32_16x16x32_bf16 v[108:111], v[234:237], v[198:201], v[108:111]
	v_mfma_f32_16x16x32_bf16 v[100:103], v[226:229], v[206:209], v[100:103]
	v_mfma_f32_16x16x32_bf16 v[92:95], v[234:237], v[206:209], v[92:95]
	v_mfma_f32_16x16x32_bf16 v[84:87], v[226:229], v[214:217], v[84:87]
	v_mfma_f32_16x16x32_bf16 v[76:79], v[234:237], v[214:217], v[76:79]
	v_mfma_f32_16x16x32_bf16 v[68:71], v[226:229], v[222:225], v[68:71]
	v_mfma_f32_16x16x32_bf16 v[64:67], v[234:237], v[222:225], v[64:67]
	s_mov_b32 m0, s64
	v_lshl_add_u64 v[138:139], v[242:243], 0, s[44:45]
	s_barrier
; #define PG8_STAGE(bufoff, gbase, v0, v1) do { \
;         __builtin_amdgcn_global_load_lds((const unsigned*)((const char*)(gbase) + (v0)), (LAS unsigned*)(lds + (bufoff) + ldsw), 16, 0, 0); \
;         __builtin_amdgcn_global_load_lds((const unsigned*)((const char*)(gbase) + (v1)), (LAS unsigned*)(lds + (bufoff) + ldsw + 8192), 16, 0, 0); } while (0)
; #define PG8_LDA(dst, b, h) do { _Pragma("unroll") for (int m = 0; m < 4; ++m) _Pragma("unroll") for (int k = 0; k < 2; ++k) dst[m][k] = *(const LAS bf16x8*)(lds + PG8_SA(b, h) + aoff + m * 2048 + k * 1024); } while (0)
; #define PG8_MMA(ai, bj, At, Bt) do { __builtin_amdgcn_s_setprio(1); _Pragma("unroll") for (int m = 0; m < 4; ++m) _Pragma("unroll") for (int n = 0; n < 2; ++n) _Pragma("unroll") for (int k = 0; k < 2; ++k) \
;         acc[ai][bj][m][n] = __builtin_amdgcn_mfma_f32_16x16x32_bf16(Bt[n][k], At[m][k], acc[ai][bj][m][n], 0, 0, 0); __builtin_amdgcn_s_setprio(0); } while (0)
; #define PG8_WAIT_V(n) asm volatile("s_waitcnt vmcnt(" #n ")" ::: "memory")
; #define PG8_WAIT_L(n) asm volatile("s_waitcnt lgkmcnt(" #n ")" ::: "memory")
; #define PG8_BAR __builtin_amdgcn_s_barrier()
; #define PG8_SCHED __builtin_amdgcn_sched_barrier(0)
; template <class Epi, class Sched>
; __device__ __forceinline__ void gemm_phase(LAS unsigned char* lds, const Sched& S, const Epi& E) {
;     ...
;         for (int t = 0; t < nt; t += 2) {
;             const bool last = (t == nt - 2);
;             const char* a1 = cA + (size_t)(t + 1) * kstep;
;             const char* a2 = last ? nA : cA + (size_t)(t + 2) * kstep; const char* b2 = last ? nB : cB + (size_t)(t + 2) * kstep;
;             const char* a3 = a2 + kstep; const char* b3 = b2 + kstep;
;             const unsigned xA0 = last ? nvA0 : vA0, xA1 = last ? nvA1 : vA1, xB0 = last ? nvB0 : vB0, xB1 = last ? nvB1 : vB1;
;             const size_t xhA = last ? nhA : hA, xhB = last ? nhB : hB;
;     ...
;             PG8_LDA(At, 1, 1); PG8_STAGE(PG8_SA(1, 0), a3, xA0, xA1);
;             PG8_BAR; PG8_WAIT_L(0); PG8_MMA(1, 0, At, B0); PG8_BAR; PG8_SCHED;
;             PG8_STAGE(PG8_SB(1, 1), b3 + xhB, xB0, xB1);
;             PG8_WAIT_V(6); PG8_BAR; PG8_MMA(1, 1, At, B1); PG8_BAR;
;         }
	ds_read_b128 v[194:197], v143 offset:49152
	ds_read_b128 v[198:201], v143 offset:50176
	ds_read_b128 v[202:205], v143 offset:51200
	ds_read_b128 v[206:209], v143 offset:52224
	ds_read_b128 v[210:213], v143 offset:53248
	ds_read_b128 v[214:217], v143 offset:54272
	ds_read_b128 v[218:221], v143 offset:55296
	ds_read_b128 v[222:225], v143 offset:56320
	global_load_lds_dwordx4 v[138:139], off
	v_lshl_add_u64 v[138:139], v[244:245], 0, s[44:45]
	s_mov_b32 m0, s65
	s_nop 0
	global_load_lds_dwordx4 v[138:139], off
	s_barrier
	s_waitcnt lgkmcnt(0)
	v_mfma_f32_16x16x32_bf16 v[60:63], v[158:161], v[194:197], v[60:63]
	v_mfma_f32_16x16x32_bf16 v[56:59], v[186:189], v[194:197], v[56:59]
	v_mfma_f32_16x16x32_bf16 v[44:47], v[158:161], v[202:205], v[44:47]
	v_mfma_f32_16x16x32_bf16 v[40:43], v[186:189], v[202:205], v[40:43]
	v_mfma_f32_16x16x32_bf16 v[28:31], v[158:161], v[210:213], v[28:31]
	v_mfma_f32_16x16x32_bf16 v[24:27], v[186:189], v[210:213], v[24:27]
	v_mfma_f32_16x16x32_bf16 v[12:15], v[158:161], v[218:221], v[12:15]
	v_mfma_f32_16x16x32_bf16 v[8:11], v[186:189], v[218:221], v[8:11]
	v_mfma_f32_16x16x32_bf16 v[60:63], v[182:185], v[198:201], v[60:63]
	v_mfma_f32_16x16x32_bf16 v[56:59], v[190:193], v[198:201], v[56:59]
	v_mfma_f32_16x16x32_bf16 v[44:47], v[182:185], v[206:209], v[44:47]
	v_mfma_f32_16x16x32_bf16 v[40:43], v[190:193], v[206:209], v[40:43]
	v_mfma_f32_16x16x32_bf16 v[28:31], v[182:185], v[214:217], v[28:31]
	v_mfma_f32_16x16x32_bf16 v[24:27], v[190:193], v[214:217], v[24:27]
	v_mfma_f32_16x16x32_bf16 v[12:15], v[182:185], v[222:225], v[12:15]
	v_mfma_f32_16x16x32_bf16 v[8:11], v[190:193], v[222:225], v[8:11]
	s_barrier
	s_add_u32 s38, s38, 0x80080
	s_addc_u32 s39, s39, 0
	s_add_i32 s21, s40, s43
	s_mov_b32 m0, s21
	s_nop 0
	global_load_lds_dwordx4 v136, s[38:39]
	s_add_i32 m0, s21, 0x2000
	s_nop 0
	global_load_lds_dwordx4 v146, s[38:39]
	s_waitcnt vmcnt(6)
	s_barrier
	v_mfma_f32_16x16x32_bf16 v[52:55], v[148:151], v[194:197], v[52:55]
	v_mfma_f32_16x16x32_bf16 v[48:51], v[230:233], v[194:197], v[48:51]
	v_mfma_f32_16x16x32_bf16 v[36:39], v[148:151], v[202:205], v[36:39]
	v_mfma_f32_16x16x32_bf16 v[32:35], v[230:233], v[202:205], v[32:35]
	v_mfma_f32_16x16x32_bf16 v[20:23], v[148:151], v[210:213], v[20:23]
	v_mfma_f32_16x16x32_bf16 v[16:19], v[230:233], v[210:213], v[16:19]
	v_mfma_f32_16x16x32_bf16 v[4:7], v[148:151], v[218:221], v[4:7]
	v_mfma_f32_16x16x32_bf16 v[0:3], v[230:233], v[218:221], v[0:3]
	v_mfma_f32_16x16x32_bf16 v[52:55], v[226:229], v[198:201], v[52:55]
	v_mfma_f32_16x16x32_bf16 v[48:51], v[234:237], v[198:201], v[48:51]
	v_mfma_f32_16x16x32_bf16 v[36:39], v[226:229], v[206:209], v[36:39]
	v_mfma_f32_16x16x32_bf16 v[32:35], v[234:237], v[206:209], v[32:35]
	v_mfma_f32_16x16x32_bf16 v[20:23], v[226:229], v[214:217], v[20:23]
	v_mfma_f32_16x16x32_bf16 v[16:19], v[234:237], v[214:217], v[16:19]
	v_mfma_f32_16x16x32_bf16 v[4:7], v[226:229], v[222:225], v[4:7]
	v_mfma_f32_16x16x32_bf16 v[0:3], v[234:237], v[222:225], v[0:3]
	s_add_i32 s15, s15, 2
	s_add_u32 s26, s26, 0x100
	s_addc_u32 s27, s27, 0
	s_add_u32 s34, s34, 0x100
	s_addc_u32 s35, s35, 0
	s_cmp_gt_u32 s15, 29
	s_cbranch_scc1 .Lrot_exit_3
	s_cmp_eq_u32 s15, 28
	s_cselect_b64 s[40:41], -1, 0
	s_and_b64 vcc, exec, s[40:41]
	v_mov_b64_e32 v[148:149], v[130:131]
	v_mov_b64_e32 v[150:151], v[128:129]
	v_mov_b32_e32 v146, v156
	v_mov_b32_e32 v136, v145
	s_mov_b64 s[38:39], s[24:25]
	s_cbranch_vccnz .Lrot_join_3
	v_mov_b64_e32 v[148:149], v[134:135]
	v_mov_b64_e32 v[150:151], v[132:133]
	v_mov_b32_e32 v146, v142
	v_mov_b32_e32 v136, v144
	s_mov_b64 s[38:39], s[34:35]
.Lrot_join_3:
	s_add_u32 s21, s26, 0xfff80080
	s_addc_u32 s69, s27, -1
	s_and_b64 s[40:41], exec, s[40:41]
	s_cselect_b32 s41, s23, s69
	s_cselect_b32 s40, s22, s21
	s_add_i32 s21, 0, 0x10000
	v_add_u32_e32 v138, s21, v155
	s_barrier
	s_branch .Lrot_body_3

; #define PG8_STAGE(bufoff, gbase, v0, v1) do { \
;         __builtin_amdgcn_global_load_lds((const unsigned*)((const char*)(gbase) + (v0)), (LAS unsigned*)(lds + (bufoff) + ldsw), 16, 0, 0); \
;         __builtin_amdgcn_global_load_lds((const unsigned*)((const char*)(gbase) + (v1)), (LAS unsigned*)(lds + (bufoff) + ldsw + 8192), 16, 0, 0); } while (0)
; #define PG8_LDA(dst, b, h) do { _Pragma("unroll") for (int m = 0; m < 4; ++m) _Pragma("unroll") for (int k = 0; k < 2; ++k) dst[m][k] = *(const LAS bf16x8*)(lds + PG8_SA(b, h) + aoff + m * 2048 + k * 1024); } while (0)
; #define PG8_LDB(dst, b, h) do { _Pragma("unroll") for (int n = 0; n < 2; ++n) _Pragma("unroll") for (int k = 0; k < 2; ++k) dst[n][k] = *(const LAS bf16x8*)(lds + PG8_SB(b, h) + boff + n * 2048 + k * 1024); } while (0)
; #define PG8_MMA(ai, bj, At, Bt) do { __builtin_amdgcn_s_setprio(1); _Pragma("unroll") for (int m = 0; m < 4; ++m) _Pragma("unroll") for (int n = 0; n < 2; ++n) _Pragma("unroll") for (int k = 0; k < 2; ++k) \
;         acc[ai][bj][m][n] = __builtin_amdgcn_mfma_f32_16x16x32_bf16(Bt[n][k], At[m][k], acc[ai][bj][m][n], 0, 0, 0); __builtin_amdgcn_s_setprio(0); } while (0)
; #define PG8_WAIT_V(n) asm volatile("s_waitcnt vmcnt(" #n ")" ::: "memory")
; #define PG8_WAIT_L(n) asm volatile("s_waitcnt lgkmcnt(" #n ")" ::: "memory")
; #define PG8_BAR __builtin_amdgcn_s_barrier()
; #define PG8_SCHED __builtin_amdgcn_sched_barrier(0)
; template <class Epi, class Sched>
; __device__ __forceinline__ void gemm_phase(LAS unsigned char* lds, const Sched& S, const Epi& E) {
;     ...
;             PG8_LDB(B0, 0, 0); PG8_SCHED; PG8_LDA(At, 0, 0); PG8_STAGE(PG8_SA(1, 1), a1 + hA, vA0, vA1);
;             PG8_WAIT_L(8); PG8_BAR; PG8_WAIT_L(0); PG8_MMA(0, 0, At, B0); PG8_BAR; PG8_SCHED;
;             PG8_LDB(B1, 0, 1); PG8_STAGE(PG8_SB(0, 0), b2, xB0, xB1);
;             PG8_BAR; PG8_WAIT_L(0); PG8_MMA(0, 1, At, B1); PG8_BAR;
;             PG8_LDA(At, 0, 1); PG8_STAGE(PG8_SA(0, 0), a2, xA0, xA1);
;             PG8_BAR; PG8_WAIT_L(0); PG8_MMA(1, 0, At, B0); PG8_BAR; PG8_SCHED;
;             PG8_STAGE(PG8_SB(0, 1), b2 + xhB, xB0, xB1);
;             PG8_WAIT_V(6); PG8_BAR; PG8_MMA(1, 1, At, B1); PG8_BAR;
.Lrot_body_4:
	ds_read_b128 v[150:153], v138
	ds_read_b128 v[154:157], v138 offset:1024
	ds_read_b128 v[158:161], v138 offset:2048
	ds_read_b128 v[182:185], v138 offset:3072
	v_lshl_add_u64 v[138:139], s[24:25], 0, v[136:137]
	s_add_i32 m0, s49, 0xc000
	ds_read_b128 v[186:189], v148
	ds_read_b128 v[190:193], v148 offset:1024
	ds_read_b128 v[194:197], v148 offset:2048
	ds_read_b128 v[198:201], v148 offset:3072
	ds_read_b128 v[202:205], v148 offset:4096
	ds_read_b128 v[206:209], v148 offset:5120
	ds_read_b128 v[210:213], v148 offset:6144
	ds_read_b128 v[214:217], v148 offset:7168
	global_load_lds_dwordx4 v[138:139], off
	v_lshl_add_u64 v[138:139], s[24:25], 0, v[132:133]
	s_add_i32 m0, s49, 0xe000
	s_nop 0
	global_load_lds_dwordx4 v[138:139], off
	s_waitcnt lgkmcnt(8)
	s_barrier
	s_waitcnt lgkmcnt(0)
	v_mfma_f32_16x16x32_bf16 v[124:127], v[150:153], v[186:189], v[124:127]
	v_mfma_f32_16x16x32_bf16 v[120:123], v[158:161], v[186:189], v[120:123]
	v_mfma_f32_16x16x32_bf16 v[108:111], v[150:153], v[194:197], v[108:111]
	v_mfma_f32_16x16x32_bf16 v[104:107], v[158:161], v[194:197], v[104:107]
	v_mfma_f32_16x16x32_bf16 v[100:103], v[150:153], v[202:205], v[100:103]
	v_mfma_f32_16x16x32_bf16 v[96:99], v[158:161], v[202:205], v[96:99]
	v_mfma_f32_16x16x32_bf16 v[84:87], v[150:153], v[210:213], v[84:87]
	v_mfma_f32_16x16x32_bf16 v[80:83], v[158:161], v[210:213], v[80:83]
	v_mfma_f32_16x16x32_bf16 v[124:127], v[154:157], v[190:193], v[124:127]
	v_mfma_f32_16x16x32_bf16 v[120:123], v[182:185], v[190:193], v[120:123]
	v_mfma_f32_16x16x32_bf16 v[108:111], v[154:157], v[198:201], v[108:111]
	v_mfma_f32_16x16x32_bf16 v[104:107], v[182:185], v[198:201], v[104:107]
	v_mfma_f32_16x16x32_bf16 v[100:103], v[154:157], v[206:209], v[100:103]
	v_mfma_f32_16x16x32_bf16 v[96:99], v[182:185], v[206:209], v[96:99]
	v_mfma_f32_16x16x32_bf16 v[84:87], v[154:157], v[214:217], v[84:87]
	v_mfma_f32_16x16x32_bf16 v[80:83], v[182:185], v[214:217], v[80:83]
	s_barrier
	s_add_i32 s82, 0, 0x14000
	v_add_u32_e32 v138, s82, v147
	s_add_i32 s15, s15, s48
	ds_read_b128 v[218:221], v138
	ds_read_b128 v[222:225], v138 offset:1024
	ds_read_b128 v[226:229], v138 offset:2048
	ds_read_b128 v[230:233], v138 offset:3072
	v_lshl_add_u64 v[138:139], s[34:35], 0, v[142:143]
	s_mov_b32 m0, s15
	v_lshl_add_u64 v[140:141], s[34:35], 0, v[134:135]
	global_load_lds_dwordx4 v[138:139], off
	s_add_i32 m0, s15, 0x2000
	s_nop 0
	global_load_lds_dwordx4 v[140:141], off
	s_barrier
	s_waitcnt lgkmcnt(0)
	v_mfma_f32_16x16x32_bf16 v[116:119], v[218:221], v[186:189], v[116:119]
	v_mfma_f32_16x16x32_bf16 v[112:115], v[226:229], v[186:189], v[112:115]
	v_mfma_f32_16x16x32_bf16 v[92:95], v[218:221], v[194:197], v[92:95]
	v_mfma_f32_16x16x32_bf16 v[88:91], v[226:229], v[194:197], v[88:91]
	v_mfma_f32_16x16x32_bf16 v[76:79], v[218:221], v[202:205], v[76:79]
	v_mfma_f32_16x16x32_bf16 v[72:75], v[226:229], v[202:205], v[72:75]
	v_mfma_f32_16x16x32_bf16 v[68:71], v[218:221], v[210:213], v[68:71]
	v_mfma_f32_16x16x32_bf16 v[64:67], v[226:229], v[210:213], v[64:67]
	v_mfma_f32_16x16x32_bf16 v[116:119], v[222:225], v[190:193], v[116:119]
	v_mfma_f32_16x16x32_bf16 v[112:115], v[230:233], v[190:193], v[112:115]
	v_mfma_f32_16x16x32_bf16 v[92:95], v[222:225], v[198:201], v[92:95]
	v_mfma_f32_16x16x32_bf16 v[88:91], v[230:233], v[198:201], v[88:91]
	v_mfma_f32_16x16x32_bf16 v[76:79], v[222:225], v[206:209], v[76:79]
	v_mfma_f32_16x16x32_bf16 v[72:75], v[230:233], v[206:209], v[72:75]
	v_mfma_f32_16x16x32_bf16 v[68:71], v[222:225], v[214:217], v[68:71]
	v_mfma_f32_16x16x32_bf16 v[64:67], v[230:233], v[214:217], v[64:67]
	s_mov_b32 m0, s49
	v_lshl_add_u64 v[234:235], s[38:39], 0, v[142:143]
	s_barrier
	ds_read_b128 v[186:189], v148 offset:16384
	ds_read_b128 v[190:193], v148 offset:17408
	ds_read_b128 v[194:197], v148 offset:18432
	ds_read_b128 v[198:201], v148 offset:19456
	ds_read_b128 v[202:205], v148 offset:20480
	ds_read_b128 v[206:209], v148 offset:21504
	ds_read_b128 v[210:213], v148 offset:22528
	ds_read_b128 v[214:217], v148 offset:23552
	global_load_lds_dwordx4 v[234:235], off
	v_lshl_add_u64 v[236:237], s[38:39], 0, v[134:135]
	s_mov_b32 m0, s50
	s_nop 0
	global_load_lds_dwordx4 v[236:237], off
	s_barrier
	s_waitcnt lgkmcnt(0)
	v_mfma_f32_16x16x32_bf16 v[60:63], v[150:153], v[186:189], v[60:63]
	v_mfma_f32_16x16x32_bf16 v[56:59], v[158:161], v[186:189], v[56:59]
	v_mfma_f32_16x16x32_bf16 v[44:47], v[150:153], v[194:197], v[44:47]
	v_mfma_f32_16x16x32_bf16 v[40:43], v[158:161], v[194:197], v[40:43]
	v_mfma_f32_16x16x32_bf16 v[28:31], v[150:153], v[202:205], v[28:31]
	v_mfma_f32_16x16x32_bf16 v[24:27], v[158:161], v[202:205], v[24:27]
	v_mfma_f32_16x16x32_bf16 v[12:15], v[150:153], v[210:213], v[12:15]
	v_mfma_f32_16x16x32_bf16 v[8:11], v[158:161], v[210:213], v[8:11]
	v_mfma_f32_16x16x32_bf16 v[60:63], v[154:157], v[190:193], v[60:63]
	v_mfma_f32_16x16x32_bf16 v[56:59], v[182:185], v[190:193], v[56:59]
	v_mfma_f32_16x16x32_bf16 v[44:47], v[154:157], v[198:201], v[44:47]
	v_mfma_f32_16x16x32_bf16 v[40:43], v[182:185], v[198:201], v[40:43]
	v_mfma_f32_16x16x32_bf16 v[28:31], v[154:157], v[206:209], v[28:31]
	v_mfma_f32_16x16x32_bf16 v[24:27], v[182:185], v[206:209], v[24:27]
	v_mfma_f32_16x16x32_bf16 v[12:15], v[154:157], v[214:217], v[12:15]
	v_mfma_f32_16x16x32_bf16 v[8:11], v[182:185], v[214:217], v[8:11]
	s_barrier
	s_add_u32 s70, s34, 0x200000
	s_addc_u32 s71, s35, 0
	s_add_i32 s15, s82, s48
	v_lshl_add_u64 v[150:151], s[70:71], 0, v[142:143]
	s_mov_b32 m0, s15
	s_nop 0
	global_load_lds_dwordx4 v[150:151], off
	v_lshl_add_u64 v[150:151], s[70:71], 0, v[134:135]
	s_add_i32 m0, s15, 0x2000
	s_nop 0
	global_load_lds_dwordx4 v[150:151], off
	s_waitcnt vmcnt(6)
	s_barrier
; #define PG8_STAGE(bufoff, gbase, v0, v1) do { \
;         __builtin_amdgcn_global_load_lds((const unsigned*)((const char*)(gbase) + (v0)), (LAS unsigned*)(lds + (bufoff) + ldsw), 16, 0, 0); \
;         __builtin_amdgcn_global_load_lds((const unsigned*)((const char*)(gbase) + (v1)), (LAS unsigned*)(lds + (bufoff) + ldsw + 8192), 16, 0, 0); } while (0)
; #define PG8_LDA(dst, b, h) do { _Pragma("unroll") for (int m = 0; m < 4; ++m) _Pragma("unroll") for (int k = 0; k < 2; ++k) dst[m][k] = *(const LAS bf16x8*)(lds + PG8_SA(b, h) + aoff + m * 2048 + k * 1024); } while (0)
; #define PG8_LDB(dst, b, h) do { _Pragma("unroll") for (int n = 0; n < 2; ++n) _Pragma("unroll") for (int k = 0; k < 2; ++k) dst[n][k] = *(const LAS bf16x8*)(lds + PG8_SB(b, h) + boff + n * 2048 + k * 1024); } while (0)
; #define PG8_MMA(ai, bj, At, Bt) do { __builtin_amdgcn_s_setprio(1); _Pragma("unroll") for (int m = 0; m < 4; ++m) _Pragma("unroll") for (int n = 0; n < 2; ++n) _Pragma("unroll") for (int k = 0; k < 2; ++k) \
;         acc[ai][bj][m][n] = __builtin_amdgcn_mfma_f32_16x16x32_bf16(Bt[n][k], At[m][k], acc[ai][bj][m][n], 0, 0, 0); __builtin_amdgcn_s_setprio(0); } while (0)
; #define PG8_WAIT_V(n) asm volatile("s_waitcnt vmcnt(" #n ")" ::: "memory")
; #define PG8_WAIT_L(n) asm volatile("s_waitcnt lgkmcnt(" #n ")" ::: "memory")
; #define PG8_BAR __builtin_amdgcn_s_barrier()
; #define PG8_SCHED __builtin_amdgcn_sched_barrier(0)
; template <class Epi, class Sched>
; __device__ __forceinline__ void gemm_phase(LAS unsigned char* lds, const Sched& S, const Epi& E) {
;     ...
;             PG8_WAIT_V(6); PG8_BAR; PG8_MMA(1, 1, At, B1); PG8_BAR;
;             PG8_LDB(B0, 1, 0); PG8_SCHED; PG8_LDA(At, 1, 0); PG8_STAGE(PG8_SA(0, 1), a2 + xhA, xA0, xA1);
;             PG8_WAIT_L(8); PG8_BAR; PG8_WAIT_L(0); PG8_MMA(0, 0, At, B0); PG8_BAR; PG8_SCHED;
;             PG8_LDB(B1, 1, 1); PG8_STAGE(PG8_SB(1, 0), b3, xB0, xB1);
;             PG8_BAR; PG8_WAIT_L(0); PG8_MMA(0, 1, At, B1); PG8_BAR;
;             PG8_LDA(At, 1, 1); PG8_STAGE(PG8_SA(1, 0), a3, xA0, xA1);
;             PG8_BAR; PG8_WAIT_L(0); PG8_MMA(1, 0, At, B0); PG8_BAR; PG8_SCHED;
	v_mfma_f32_16x16x32_bf16 v[52:55], v[218:221], v[186:189], v[52:55]
	v_mfma_f32_16x16x32_bf16 v[48:51], v[226:229], v[186:189], v[48:51]
	v_mfma_f32_16x16x32_bf16 v[36:39], v[218:221], v[194:197], v[36:39]
	v_mfma_f32_16x16x32_bf16 v[32:35], v[226:229], v[194:197], v[32:35]
	v_mfma_f32_16x16x32_bf16 v[20:23], v[218:221], v[202:205], v[20:23]
	v_mfma_f32_16x16x32_bf16 v[16:19], v[226:229], v[202:205], v[16:19]
	v_mfma_f32_16x16x32_bf16 v[4:7], v[218:221], v[210:213], v[4:7]
	v_mfma_f32_16x16x32_bf16 v[0:3], v[226:229], v[210:213], v[0:3]
	v_mfma_f32_16x16x32_bf16 v[52:55], v[222:225], v[190:193], v[52:55]
	v_mfma_f32_16x16x32_bf16 v[48:51], v[230:233], v[190:193], v[48:51]
	v_mfma_f32_16x16x32_bf16 v[36:39], v[222:225], v[198:201], v[36:39]
	v_mfma_f32_16x16x32_bf16 v[32:35], v[230:233], v[198:201], v[32:35]
	v_mfma_f32_16x16x32_bf16 v[20:23], v[222:225], v[206:209], v[20:23]
	v_mfma_f32_16x16x32_bf16 v[16:19], v[230:233], v[206:209], v[16:19]
	v_mfma_f32_16x16x32_bf16 v[4:7], v[222:225], v[214:217], v[4:7]
	v_mfma_f32_16x16x32_bf16 v[0:3], v[230:233], v[214:217], v[0:3]
	s_add_i32 s15, 0, 0x18000
	v_add_u32_e32 v149, s15, v147
	s_barrier
	ds_read_b128 v[150:153], v149
	ds_read_b128 v[154:157], v149 offset:1024
	ds_read_b128 v[158:161], v149 offset:2048
	ds_read_b128 v[182:185], v149 offset:3072
	s_add_u32 s38, s38, 0x200000
	s_addc_u32 s39, s39, 0
	s_mov_b32 m0, s51
	v_lshl_add_u64 v[218:219], s[38:39], 0, v[142:143]
	ds_read_b128 v[186:189], v148 offset:32768
	ds_read_b128 v[190:193], v148 offset:33792
	ds_read_b128 v[194:197], v148 offset:34816
	ds_read_b128 v[198:201], v148 offset:35840
	ds_read_b128 v[202:205], v148 offset:36864
	ds_read_b128 v[206:209], v148 offset:37888
	ds_read_b128 v[210:213], v148 offset:38912
	ds_read_b128 v[214:217], v148 offset:39936
	global_load_lds_dwordx4 v[218:219], off
	v_lshl_add_u64 v[218:219], s[38:39], 0, v[134:135]
	s_mov_b32 m0, s54
	s_nop 0
	global_load_lds_dwordx4 v[218:219], off
	s_waitcnt lgkmcnt(8)
	s_barrier
	s_waitcnt lgkmcnt(0)
	v_mfma_f32_16x16x32_bf16 v[124:127], v[150:153], v[186:189], v[124:127]
	v_mfma_f32_16x16x32_bf16 v[120:123], v[158:161], v[186:189], v[120:123]
	v_mfma_f32_16x16x32_bf16 v[108:111], v[150:153], v[194:197], v[108:111]
	v_mfma_f32_16x16x32_bf16 v[104:107], v[158:161], v[194:197], v[104:107]
	v_mfma_f32_16x16x32_bf16 v[100:103], v[150:153], v[202:205], v[100:103]
	v_mfma_f32_16x16x32_bf16 v[96:99], v[158:161], v[202:205], v[96:99]
	v_mfma_f32_16x16x32_bf16 v[84:87], v[150:153], v[210:213], v[84:87]
	v_mfma_f32_16x16x32_bf16 v[80:83], v[158:161], v[210:213], v[80:83]
	v_mfma_f32_16x16x32_bf16 v[124:127], v[154:157], v[190:193], v[124:127]
	v_mfma_f32_16x16x32_bf16 v[120:123], v[182:185], v[190:193], v[120:123]
	v_mfma_f32_16x16x32_bf16 v[108:111], v[154:157], v[198:201], v[108:111]
	v_mfma_f32_16x16x32_bf16 v[104:107], v[182:185], v[198:201], v[104:107]
	v_mfma_f32_16x16x32_bf16 v[100:103], v[154:157], v[206:209], v[100:103]
	v_mfma_f32_16x16x32_bf16 v[96:99], v[182:185], v[206:209], v[96:99]
	v_mfma_f32_16x16x32_bf16 v[84:87], v[154:157], v[214:217], v[84:87]
	v_mfma_f32_16x16x32_bf16 v[80:83], v[182:185], v[214:217], v[80:83]
	s_barrier
	s_add_i32 s38, 0, 0x1c000
	s_add_i32 s15, s15, s48
	v_add_u32_e32 v149, s38, v147
	v_lshl_add_u64 v[138:139], v[138:139], 0, s[44:45]
	s_mov_b32 m0, s15
	ds_read_b128 v[218:221], v149
	ds_read_b128 v[222:225], v149 offset:1024
	ds_read_b128 v[226:229], v149 offset:2048
	ds_read_b128 v[230:233], v149 offset:3072
	global_load_lds_dwordx4 v[138:139], off
	v_lshl_add_u64 v[138:139], v[140:141], 0, s[44:45]
	s_add_i32 m0, s15, 0x2000
	s_nop 0
	global_load_lds_dwordx4 v[138:139], off
	s_barrier
	s_waitcnt lgkmcnt(0)
	v_mfma_f32_16x16x32_bf16 v[116:119], v[218:221], v[186:189], v[116:119]
	v_mfma_f32_16x16x32_bf16 v[112:115], v[226:229], v[186:189], v[112:115]
	v_mfma_f32_16x16x32_bf16 v[92:95], v[218:221], v[194:197], v[92:95]
	v_mfma_f32_16x16x32_bf16 v[88:91], v[226:229], v[194:197], v[88:91]
	v_mfma_f32_16x16x32_bf16 v[76:79], v[218:221], v[202:205], v[76:79]
	v_mfma_f32_16x16x32_bf16 v[72:75], v[226:229], v[202:205], v[72:75]
	v_mfma_f32_16x16x32_bf16 v[68:71], v[218:221], v[210:213], v[68:71]
	v_mfma_f32_16x16x32_bf16 v[64:67], v[226:229], v[210:213], v[64:67]
	v_mfma_f32_16x16x32_bf16 v[116:119], v[222:225], v[190:193], v[116:119]
	v_mfma_f32_16x16x32_bf16 v[112:115], v[230:233], v[190:193], v[112:115]
	v_mfma_f32_16x16x32_bf16 v[92:95], v[222:225], v[198:201], v[92:95]
	v_mfma_f32_16x16x32_bf16 v[88:91], v[230:233], v[198:201], v[88:91]
	v_mfma_f32_16x16x32_bf16 v[76:79], v[222:225], v[206:209], v[76:79]
	v_mfma_f32_16x16x32_bf16 v[72:75], v[230:233], v[206:209], v[72:75]
	v_mfma_f32_16x16x32_bf16 v[68:71], v[222:225], v[214:217], v[68:71]
	v_mfma_f32_16x16x32_bf16 v[64:67], v[230:233], v[214:217], v[64:67]
	s_mov_b32 m0, s65
	v_lshl_add_u64 v[138:139], v[234:235], 0, s[44:45]
	s_barrier
; #define PG8_STAGE(bufoff, gbase, v0, v1) do { \
;         __builtin_amdgcn_global_load_lds((const unsigned*)((const char*)(gbase) + (v0)), (LAS unsigned*)(lds + (bufoff) + ldsw), 16, 0, 0); \
;         __builtin_amdgcn_global_load_lds((const unsigned*)((const char*)(gbase) + (v1)), (LAS unsigned*)(lds + (bufoff) + ldsw + 8192), 16, 0, 0); } while (0)
; #define PG8_LDA(dst, b, h) do { _Pragma("unroll") for (int m = 0; m < 4; ++m) _Pragma("unroll") for (int k = 0; k < 2; ++k) dst[m][k] = *(const LAS bf16x8*)(lds + PG8_SA(b, h) + aoff + m * 2048 + k * 1024); } while (0)
; #define PG8_MMA(ai, bj, At, Bt) do { __builtin_amdgcn_s_setprio(1); _Pragma("unroll") for (int m = 0; m < 4; ++m) _Pragma("unroll") for (int n = 0; n < 2; ++n) _Pragma("unroll") for (int k = 0; k < 2; ++k) \
;         acc[ai][bj][m][n] = __builtin_amdgcn_mfma_f32_16x16x32_bf16(Bt[n][k], At[m][k], acc[ai][bj][m][n], 0, 0, 0); __builtin_amdgcn_s_setprio(0); } while (0)
; #define PG8_WAIT_V(n) asm volatile("s_waitcnt vmcnt(" #n ")" ::: "memory")
; #define PG8_WAIT_L(n) asm volatile("s_waitcnt lgkmcnt(" #n ")" ::: "memory")
; #define PG8_BAR __builtin_amdgcn_s_barrier()
; #define PG8_SCHED __builtin_amdgcn_sched_barrier(0)
; template <class Epi, class Sched>
; __device__ __forceinline__ void gemm_phase(LAS unsigned char* lds, const Sched& S, const Epi& E) {
;     ...
;         for (int t = 0; t < nt; t += 2) {
;             const bool last = (t == nt - 2);
;             const char* a1 = cA + (size_t)(t + 1) * kstep;
;             const char* a2 = last ? nA : cA + (size_t)(t + 2) * kstep; const char* b2 = last ? nB : cB + (size_t)(t + 2) * kstep;
;             const char* a3 = a2 + kstep; const char* b3 = b2 + kstep;
;             const unsigned xA0 = last ? nvA0 : vA0, xA1 = last ? nvA1 : vA1, xB0 = last ? nvB0 : vB0, xB1 = last ? nvB1 : vB1;
;             const size_t xhA = last ? nhA : hA, xhB = last ? nhB : hB;
;     ...
;             PG8_LDA(At, 1, 1); PG8_STAGE(PG8_SA(1, 0), a3, xA0, xA1);
;             PG8_BAR; PG8_WAIT_L(0); PG8_MMA(1, 0, At, B0); PG8_BAR; PG8_SCHED;
;             PG8_STAGE(PG8_SB(1, 1), b3 + xhB, xB0, xB1);
;             PG8_WAIT_V(6); PG8_BAR; PG8_MMA(1, 1, At, B1); PG8_BAR;
;         }
	ds_read_b128 v[186:189], v148 offset:49152
	ds_read_b128 v[190:193], v148 offset:50176
	ds_read_b128 v[194:197], v148 offset:51200
	ds_read_b128 v[198:201], v148 offset:52224
	ds_read_b128 v[202:205], v148 offset:53248
	ds_read_b128 v[206:209], v148 offset:54272
	ds_read_b128 v[210:213], v148 offset:55296
	ds_read_b128 v[214:217], v148 offset:56320
	global_load_lds_dwordx4 v[138:139], off
	v_lshl_add_u64 v[138:139], v[236:237], 0, s[44:45]
	s_mov_b32 m0, s66
	s_nop 0
	global_load_lds_dwordx4 v[138:139], off
	s_barrier
	s_waitcnt lgkmcnt(0)
	v_mfma_f32_16x16x32_bf16 v[60:63], v[150:153], v[186:189], v[60:63]
	v_mfma_f32_16x16x32_bf16 v[56:59], v[158:161], v[186:189], v[56:59]
	v_mfma_f32_16x16x32_bf16 v[44:47], v[150:153], v[194:197], v[44:47]
	v_mfma_f32_16x16x32_bf16 v[40:43], v[158:161], v[194:197], v[40:43]
	v_mfma_f32_16x16x32_bf16 v[28:31], v[150:153], v[202:205], v[28:31]
	v_mfma_f32_16x16x32_bf16 v[24:27], v[158:161], v[202:205], v[24:27]
	v_mfma_f32_16x16x32_bf16 v[12:15], v[150:153], v[210:213], v[12:15]
	v_mfma_f32_16x16x32_bf16 v[8:11], v[158:161], v[210:213], v[8:11]
	v_mfma_f32_16x16x32_bf16 v[60:63], v[154:157], v[190:193], v[60:63]
	v_mfma_f32_16x16x32_bf16 v[56:59], v[182:185], v[190:193], v[56:59]
	v_mfma_f32_16x16x32_bf16 v[44:47], v[154:157], v[198:201], v[44:47]
	v_mfma_f32_16x16x32_bf16 v[40:43], v[182:185], v[198:201], v[40:43]
	v_mfma_f32_16x16x32_bf16 v[28:31], v[154:157], v[206:209], v[28:31]
	v_mfma_f32_16x16x32_bf16 v[24:27], v[182:185], v[206:209], v[24:27]
	v_mfma_f32_16x16x32_bf16 v[12:15], v[154:157], v[214:217], v[12:15]
	v_mfma_f32_16x16x32_bf16 v[8:11], v[182:185], v[214:217], v[8:11]
	s_barrier
	s_add_u32 s34, s34, 0x200080
	s_addc_u32 s35, s35, 0
	s_add_i32 s15, s38, s48
	v_lshl_add_u64 v[138:139], s[34:35], 0, v[142:143]
	s_mov_b32 m0, s15
	v_lshl_add_u64 v[134:135], s[34:35], 0, v[134:135]
	global_load_lds_dwordx4 v[138:139], off
	s_add_i32 m0, s15, 0x2000
	s_nop 0
	global_load_lds_dwordx4 v[134:135], off
	s_waitcnt vmcnt(6)
	s_barrier
	v_mfma_f32_16x16x32_bf16 v[52:55], v[218:221], v[186:189], v[52:55]
	v_mfma_f32_16x16x32_bf16 v[48:51], v[226:229], v[186:189], v[48:51]
	v_mfma_f32_16x16x32_bf16 v[36:39], v[218:221], v[194:197], v[36:39]
	v_mfma_f32_16x16x32_bf16 v[32:35], v[226:229], v[194:197], v[32:35]
	v_mfma_f32_16x16x32_bf16 v[20:23], v[218:221], v[202:205], v[20:23]
	v_mfma_f32_16x16x32_bf16 v[16:19], v[226:229], v[202:205], v[16:19]
	v_mfma_f32_16x16x32_bf16 v[4:7], v[218:221], v[210:213], v[4:7]
	v_mfma_f32_16x16x32_bf16 v[0:3], v[226:229], v[210:213], v[0:3]
	v_mfma_f32_16x16x32_bf16 v[52:55], v[222:225], v[190:193], v[52:55]
	v_mfma_f32_16x16x32_bf16 v[48:51], v[230:233], v[190:193], v[48:51]
	v_mfma_f32_16x16x32_bf16 v[36:39], v[222:225], v[198:201], v[36:39]
	v_mfma_f32_16x16x32_bf16 v[32:35], v[230:233], v[198:201], v[32:35]
	v_mfma_f32_16x16x32_bf16 v[20:23], v[222:225], v[206:209], v[20:23]
	v_mfma_f32_16x16x32_bf16 v[16:19], v[230:233], v[206:209], v[16:19]
	v_mfma_f32_16x16x32_bf16 v[4:7], v[222:225], v[214:217], v[4:7]
	v_mfma_f32_16x16x32_bf16 v[0:3], v[230:233], v[214:217], v[0:3]
	s_add_i32 s11, s11, 2
	s_add_u32 s24, s24, 0x100
	s_addc_u32 s25, s25, 0
	s_add_u32 s26, s26, 0x100
	s_addc_u32 s27, s27, 0
	s_cmpk_gt_u32 s11, 0x7d
	s_cbranch_scc1 .Lrot_exit_4
	s_cmpk_eq_i32 s11, 0x7c
	s_cselect_b64 s[38:39], -1, 0
	s_and_b64 vcc, exec, s[38:39]
	v_mov_b64_e32 v[134:135], v[130:131]
	v_mov_b64_e32 v[142:143], v[128:129]
	s_mov_b64 s[34:35], s[22:23]
	s_cbranch_vccnz .Lrot_join_4
	v_mov_b64_e32 v[134:135], v[132:133]
	v_mov_b64_e32 v[142:143], v[136:137]
	s_mov_b64 s[34:35], s[26:27]
.Lrot_join_4:
	s_add_u32 s15, s24, 0xffe00080
	s_addc_u32 s70, s25, -1
	s_and_b64 s[38:39], exec, s[38:39]
	s_cselect_b32 s39, s21, s70
	s_cselect_b32 s38, s20, s15
	s_add_i32 s15, 0, 0x10000
	v_add_u32_e32 v138, s15, v147
	s_barrier
	s_branch .Lrot_body_4
